# v11 + shorter DPP wave sums (row_bcast) + GEMM first-iteration peel (no accumulator zeroing)
# speedup vs baseline: 1.0004x; 1.0004x over previous
; #define GAS __attribute__((address_space(1)))
; DI unsigned pk2(float lo, float hi) { f32x2_t v = {lo, hi}; bf16x2_t b = __builtin_convertvector(v, bf16x2_t); return __builtin_bit_cast(unsigned, b); }
; DI void phase_e(const Ctx& C, int nslab, int has_post, int pl, int ps, float pw, int has_pre, int ql, int qs, int nrows,
;                 const GAS float* xsrc, const GAS float* csrc, GAS float* xdst, GAS float* cdst, bool xs16, bool xd16) {
;     ...
;         if (has_pre) {
;             float ss = 0.f;
; #pragma unroll
;             for (int j = 0; j < 4; ++j) ss += (v[j][0] * v[j][0] + v[j][1] * v[j][1]) + (v[j][2] * v[j][2] + v[j][3] * v[j][3]);
;             const float r = rsqrtf(wave_sum(ss) * (1.0f / 1024.0f) + EPS);
; #pragma unroll
;             for (int j = 0; j < 4; ++j) { const f32x4 h = ((v[j] * r) * gpr[j]) * (1.0f + sc[j]) + sh[j];
;                 u32x2 w; w.x = pk2(h[0], h[1]); w.y = pk2(h[2], h[3]); *(GAS u32x2*)(H + (size_t)row * 1024 + 256 * j + 4 * lane) = w; }
;         }
.LBB0_189:
	v_pk_mul_f32 v[110:111], v[48:49], v[48:49]
	v_pk_mul_f32 v[112:113], v[46:47], v[46:47]
	s_ashr_i32 s3, s2, 31
	v_pk_mov_b32 v[114:115], v[112:113], v[110:111] op_sel:[1,0]
	v_mov_b32_e32 v113, v111
	v_pk_add_f32 v[110:111], v[114:115], v[112:113]
	v_pk_mul_f32 v[112:113], v[28:29], v[28:29]
	v_pk_add_f32 v[110:111], v[110:111], v[110:111] op_sel_hi:[0,1]
	v_pk_mul_f32 v[114:115], v[26:27], v[26:27]
	v_mul_f32_e32 v110, v22, v22
	v_pk_mov_b32 v[116:117], v[114:115], v[112:113] op_sel:[1,0]
	v_mov_b32_e32 v115, v113
	v_pk_add_f32 v[112:113], v[116:117], v[114:115]
	v_pk_fma_f32 v[114:115], v[22:23], v[22:23], v[110:111] op_sel_hi:[1,1,0]
	v_mul_f32_e32 v110, v24, v24
	v_pk_add_f32 v[112:113], v[112:113], v[112:113] op_sel_hi:[0,1]
	v_pk_fma_f32 v[116:117], v[24:25], v[24:25], v[110:111] op_sel_hi:[1,1,0]
	v_mul_f32_e32 v114, v18, v18
	v_mul_f32_e32 v116, v19, v19
	v_mul_f32_e32 v112, v20, v20
	v_mul_f32_e32 v110, v21, v21
	v_pk_add_f32 v[114:115], v[114:115], v[116:117]
	v_pk_add_f32 v[110:111], v[112:113], v[110:111]
	s_lshl_b64 s[2:3], s[2:3], 11
	v_pk_add_f32 v[110:111], v[114:115], v[110:111]
	v_lshl_add_u64 v[114:115], v[100:101], 0, s[2:3]
	v_add_f32_e32 v109, v110, v111
	s_nop 1
	v_add_f32_dpp v109, v109, v109 quad_perm:[1,0,3,2] row_mask:0xf bank_mask:0xf
	s_nop 1
	v_add_f32_dpp v109, v109, v109 quad_perm:[2,3,0,1] row_mask:0xf bank_mask:0xf
	s_nop 1
	v_add_f32_dpp v109, v109, v109 row_half_mirror row_mask:0xf bank_mask:0xf
	s_nop 1
	v_add_f32_dpp v109, v109, v109 row_mirror row_mask:0xf bank_mask:0xf
	s_nop 1
	v_add_f32_dpp v109, v109, v109 row_bcast:15 row_mask:0xa bank_mask:0xf
	s_nop 1
	v_add_f32_dpp v109, v109, v109 row_bcast:31 row_mask:0xc bank_mask:0xf
	s_nop 0
	v_readlane_b32 s64, v109, 63
	s_nop 1
	v_mov_b32_e32 v109, s64
	s_waitcnt lgkmcnt(0)
	s_add_i32 s6, s6, 8
	s_cmp_lt_i32 s6, s8
	s_waitcnt vmcnt(3)
	v_pk_add_f32 v[110:111], v[68:69], 1.0 op_sel_hi:[1,0]
	v_fmamk_f32 v109, v109, 0x3a800000, v108
	v_mul_f32_e32 v112, 0x4b800000, v109
	v_cmp_gt_f32_e32 vcc, s22, v109
	s_nop 1
	v_cndmask_b32_e32 v109, v109, v112, vcc
	v_rsq_f32_e32 v109, v109
	v_pk_add_f32 v[112:113], v[66:67], 1.0 op_sel_hi:[1,0]
	v_mul_f32_e32 v116, 0x45800000, v109
	v_cndmask_b32_e32 v116, v109, v116, vcc
	v_pk_mul_f32 v[48:49], v[48:49], v[116:117] op_sel_hi:[1,0]
	v_pk_mul_f32 v[46:47], v[46:47], v[116:117] op_sel_hi:[1,0]
	v_pk_mul_f32 v[48:49], v[4:5], v[48:49]
	v_pk_mul_f32 v[46:47], v[2:3], v[46:47]
	v_pk_fma_f32 v[48:49], v[110:111], v[48:49], v[64:65]
	v_pk_fma_f32 v[46:47], v[112:113], v[46:47], v[62:63]
	v_pk_mul_f32 v[28:29], v[28:29], v[116:117] op_sel_hi:[1,0]
	v_cvt_pk_bf16_f32 v46, v46, v47
	v_cvt_pk_bf16_f32 v47, v48, v49
	v_pk_mul_f32 v[26:27], v[26:27], v[116:117] op_sel_hi:[1,0]
	global_store_dwordx2 v[114:115], v[46:47], off
	v_pk_mul_f32 v[26:27], v[6:7], v[26:27]
	v_pk_mul_f32 v[28:29], v[8:9], v[28:29]
	v_pk_add_f32 v[46:47], v[60:61], 1.0 op_sel_hi:[1,0]
	v_pk_add_f32 v[48:49], v[58:59], 1.0 op_sel_hi:[1,0]
	v_pk_fma_f32 v[28:29], v[46:47], v[28:29], v[72:73]
	v_pk_fma_f32 v[26:27], v[48:49], v[26:27], v[70:71]
	v_pk_mul_f32 v[24:25], v[24:25], v[116:117] op_sel_hi:[1,0]
	v_cvt_pk_bf16_f32 v26, v26, v27
	v_cvt_pk_bf16_f32 v27, v28, v29
	v_pk_mul_f32 v[22:23], v[22:23], v[116:117] op_sel_hi:[1,0]
	global_store_dwordx2 v[114:115], v[26:27], off offset:512
	v_pk_mul_f32 v[22:23], v[10:11], v[22:23]
	v_pk_mul_f32 v[24:25], v[12:13], v[24:25]
	v_pk_add_f32 v[26:27], v[56:57], 1.0 op_sel_hi:[1,0]
	v_pk_add_f32 v[28:29], v[54:55], 1.0 op_sel_hi:[1,0]
	s_waitcnt vmcnt(3)
	v_pk_fma_f32 v[24:25], v[26:27], v[24:25], v[80:81]
	v_pk_fma_f32 v[22:23], v[28:29], v[22:23], v[78:79]
	v_pk_mul_f32 v[20:21], v[20:21], v[116:117] op_sel_hi:[1,0]
	v_cvt_pk_bf16_f32 v22, v22, v23
	v_cvt_pk_bf16_f32 v23, v24, v25
	v_pk_mul_f32 v[18:19], v[18:19], v[116:117] op_sel_hi:[1,0]
	global_store_dwordx2 v[114:115], v[22:23], off offset:1024
	v_pk_mul_f32 v[18:19], v[14:15], v[18:19]
	v_pk_mul_f32 v[20:21], v[16:17], v[20:21]
	v_pk_add_f32 v[22:23], v[52:53], 1.0 op_sel_hi:[1,0]
	v_pk_add_f32 v[24:25], v[50:51], 1.0 op_sel_hi:[1,0]
	s_waitcnt vmcnt(3)
	v_pk_fma_f32 v[20:21], v[22:23], v[20:21], v[76:77]
	v_pk_fma_f32 v[18:19], v[24:25], v[18:19], v[74:75]
	v_mov_b64_e32 v[22:23], v[38:39]
	v_cvt_pk_bf16_f32 v18, v18, v19
	v_cvt_pk_bf16_f32 v19, v20, v21
	global_store_dwordx2 v[114:115], v[18:19], off offset:1536
	v_mov_b64_e32 v[18:19], v[42:43]
	v_mov_b64_e32 v[26:27], v[34:35]
	v_mov_b64_e32 v[48:49], v[32:33]
	v_mov_b64_e32 v[20:21], v[44:45]
	v_mov_b64_e32 v[24:25], v[40:41]
	v_mov_b64_e32 v[28:29], v[36:37]
	v_mov_b64_e32 v[46:47], v[30:31]
	v_mov_b64_e32 v[42:43], v[82:83]
	v_mov_b64_e32 v[38:39], v[86:87]
	v_mov_b64_e32 v[34:35], v[90:91]
	v_mov_b64_e32 v[30:31], v[94:95]
	v_mov_b64_e32 v[44:45], v[84:85]
	v_mov_b64_e32 v[40:41], v[88:89]
	v_mov_b64_e32 v[36:37], v[92:93]
	v_mov_b64_e32 v[32:33], v[96:97]
	s_cbranch_scc0 .LBB0_194

; #define GAS __attribute__((address_space(1)))
; DI unsigned pk2(float lo, float hi) { f32x2_t v = {lo, hi}; bf16x2_t b = __builtin_convertvector(v, bf16x2_t); return __builtin_bit_cast(unsigned, b); }
; DI void phase_e(const Ctx& C, int nslab, int has_post, int pl, int ps, float pw, int has_pre, int ql, int qs, int nrows,
;                 const GAS float* xsrc, const GAS float* csrc, GAS float* xdst, GAS float* cdst, bool xs16, bool xd16) {
;     ...
;         if (has_pre) {
;             float ss = 0.f;
; #pragma unroll
;             for (int j = 0; j < 4; ++j) ss += (v[j][0] * v[j][0] + v[j][1] * v[j][1]) + (v[j][2] * v[j][2] + v[j][3] * v[j][3]);
;             const float r = rsqrtf(wave_sum(ss) * (1.0f / 1024.0f) + EPS);
; #pragma unroll
;             for (int j = 0; j < 4; ++j) { const f32x4 h = ((v[j] * r) * gpr[j]) * (1.0f + sc[j]) + sh[j];
;                 u32x2 w; w.x = pk2(h[0], h[1]); w.y = pk2(h[2], h[3]); *(GAS u32x2*)(H + (size_t)row * 1024 + 256 * j + 4 * lane) = w; }
;         }
.LBB0_424:
	v_pk_mul_f32 v[54:55], v[128:129], v[128:129]
	v_pk_mul_f32 v[56:57], v[126:127], v[126:127]
	v_pk_mul_f32 v[50:51], v[132:133], v[132:133]
	v_pk_mul_f32 v[52:53], v[130:131], v[130:131]
	v_pk_mov_b32 v[58:59], v[56:57], v[54:55] op_sel:[1,0]
	v_mov_b32_e32 v57, v55
	v_pk_add_f32 v[54:55], v[58:59], v[56:57]
	v_pk_mov_b32 v[56:57], v[52:53], v[50:51] op_sel:[1,0]
	v_mov_b32_e32 v53, v51
	v_pk_add_f32 v[50:51], v[56:57], v[52:53]
	v_pk_add_f32 v[54:55], v[54:55], v[54:55] op_sel_hi:[0,1]
	v_pk_add_f32 v[50:51], v[50:51], v[50:51] op_sel_hi:[0,1]
	v_mul_f32_e32 v50, v134, v134
	v_pk_fma_f32 v[52:53], v[134:135], v[134:135], v[50:51] op_sel_hi:[1,1,0]
	v_mul_f32_e32 v50, v136, v136
	v_pk_fma_f32 v[56:57], v[136:137], v[136:137], v[50:51] op_sel_hi:[1,1,0]
	v_mul_f32_e32 v52, v138, v138
	v_mul_f32_e32 v56, v139, v139
	v_mul_f32_e32 v54, v140, v140
	v_mul_f32_e32 v50, v141, v141
	v_pk_add_f32 v[52:53], v[52:53], v[56:57]
	v_pk_add_f32 v[50:51], v[54:55], v[50:51]
	v_pk_add_f32 v[54:55], v[66:67], 1.0 op_sel_hi:[1,0]
	v_pk_add_f32 v[50:51], v[52:53], v[50:51]
	v_pk_add_f32 v[52:53], v[68:69], 1.0 op_sel_hi:[1,0]
	v_add_f32_e32 v50, v50, v51
	s_nop 1
	v_add_f32_dpp v50, v50, v50 quad_perm:[1,0,3,2] row_mask:0xf bank_mask:0xf
	s_nop 1
	v_add_f32_dpp v50, v50, v50 quad_perm:[2,3,0,1] row_mask:0xf bank_mask:0xf
	s_nop 1
	v_add_f32_dpp v50, v50, v50 row_half_mirror row_mask:0xf bank_mask:0xf
	s_nop 1
	v_add_f32_dpp v50, v50, v50 row_mirror row_mask:0xf bank_mask:0xf
	s_nop 1
	v_add_f32_dpp v50, v50, v50 row_bcast:15 row_mask:0xa bank_mask:0xf
	s_nop 1
	v_add_f32_dpp v50, v50, v50 row_bcast:31 row_mask:0xc bank_mask:0xf
	s_nop 0
	v_readlane_b32 s64, v50, 63
	s_nop 1
	v_mov_b32_e32 v50, s64
	s_waitcnt lgkmcnt(0)
	s_add_i32 s0, s43, 8
	s_add_i32 s1, s43, -8
	s_cmp_lt_i32 s1, s27
	s_mov_b32 s43, s0
	v_mov_b64_e32 v[170:171], v[144:145]
	s_waitcnt vmcnt(3)
	v_mov_b64_e32 v[144:145], v[162:163]
	v_fmamk_f32 v50, v50, 0x3a800000, v197
	v_mul_f32_e32 v51, 0x4b800000, v50
	v_cmp_gt_f32_e32 vcc, s47, v50
	s_nop 1
	v_cndmask_b32_e32 v50, v50, v51, vcc
	v_rsq_f32_e32 v56, v50
	v_lshl_add_u64 v[50:51], v[158:159], 0, s[2:3]
	v_mul_f32_e32 v57, 0x45800000, v56
	v_cndmask_b32_e32 v56, v56, v57, vcc
	v_pk_mul_f32 v[58:59], v[128:129], v[56:57] op_sel_hi:[1,0]
	v_pk_mul_f32 v[60:61], v[126:127], v[56:57] op_sel_hi:[1,0]
	v_pk_mul_f32 v[58:59], v[12:13], v[58:59]
	v_pk_mul_f32 v[60:61], v[10:11], v[60:61]
	v_pk_fma_f32 v[52:53], v[52:53], v[58:59], v[72:73]
	v_pk_fma_f32 v[54:55], v[54:55], v[60:61], v[70:71]
	v_pk_mul_f32 v[126:127], v[132:133], v[56:57] op_sel_hi:[1,0]
	v_pk_mul_f32 v[128:129], v[130:131], v[56:57] op_sel_hi:[1,0]
	v_cvt_pk_bf16_f32 v54, v54, v55
	v_cvt_pk_bf16_f32 v55, v52, v53
	v_pk_mul_f32 v[128:129], v[14:15], v[128:129]
	global_store_dwordx2 v[50:51], v[54:55], off
	v_pk_mul_f32 v[52:53], v[16:17], v[126:127]
	v_pk_add_f32 v[54:55], v[76:77], 1.0 op_sel_hi:[1,0]
	v_pk_add_f32 v[58:59], v[74:75], 1.0 op_sel_hi:[1,0]
	v_pk_fma_f32 v[52:53], v[54:55], v[52:53], v[80:81]
	v_pk_fma_f32 v[54:55], v[58:59], v[128:129], v[78:79]
	v_pk_add_f32 v[58:59], v[84:85], 1.0 op_sel_hi:[1,0]
	v_cvt_pk_bf16_f32 v54, v54, v55
	v_cvt_pk_bf16_f32 v55, v52, v53
	global_store_dwordx2 v[50:51], v[54:55], off offset:512
	v_pk_mul_f32 v[52:53], v[136:137], v[56:57] op_sel_hi:[1,0]
	v_pk_mul_f32 v[54:55], v[134:135], v[56:57] op_sel_hi:[1,0]
	v_pk_mul_f32 v[52:53], v[28:29], v[52:53]
	v_pk_mul_f32 v[54:55], v[26:27], v[54:55]
	v_pk_add_f32 v[60:61], v[82:83], 1.0 op_sel_hi:[1,0]
	s_waitcnt vmcnt(3)
	v_pk_fma_f32 v[52:53], v[58:59], v[52:53], v[92:93]
	v_pk_fma_f32 v[54:55], v[60:61], v[54:55], v[90:91]
	v_pk_add_f32 v[58:59], v[62:63], 1.0 op_sel_hi:[1,0]
	v_cvt_pk_bf16_f32 v54, v54, v55
	v_cvt_pk_bf16_f32 v55, v52, v53
	global_store_dwordx2 v[50:51], v[54:55], off offset:1024
	v_pk_mul_f32 v[52:53], v[140:141], v[56:57] op_sel_hi:[1,0]
	v_pk_mul_f32 v[54:55], v[138:139], v[56:57] op_sel_hi:[1,0]
	v_pk_mul_f32 v[52:53], v[32:33], v[52:53]
	v_pk_mul_f32 v[54:55], v[30:31], v[54:55]
	v_pk_add_f32 v[56:57], v[64:65], 1.0 op_sel_hi:[1,0]
	s_waitcnt vmcnt(3)
	v_pk_fma_f32 v[54:55], v[58:59], v[54:55], v[86:87]
	v_pk_fma_f32 v[52:53], v[56:57], v[52:53], v[88:89]
	v_cvt_pk_bf16_f32 v54, v54, v55
	v_cvt_pk_bf16_f32 v55, v52, v53
	global_store_dwordx2 v[50:51], v[54:55], off offset:1536
	v_mov_b64_e32 v[52:53], v[48:49]
	v_mov_b64_e32 v[56:57], v[44:45]
	v_mov_b64_e32 v[60:61], v[40:41]
	v_mov_b64_e32 v[128:129], v[36:37]
	v_mov_b64_e32 v[50:51], v[46:47]
	v_mov_b64_e32 v[54:55], v[42:43]
	v_mov_b64_e32 v[58:59], v[38:39]
	v_mov_b64_e32 v[126:127], v[34:35]
	v_mov_b64_e32 v[46:47], v[110:111]
	v_mov_b64_e32 v[42:43], v[114:115]
	v_mov_b64_e32 v[38:39], v[118:119]
	v_mov_b64_e32 v[34:35], v[122:123]
	v_mov_b64_e32 v[48:49], v[112:113]
	v_mov_b64_e32 v[44:45], v[116:117]
	v_mov_b64_e32 v[40:41], v[120:121]
	v_mov_b64_e32 v[36:37], v[124:125]
	v_mov_b64_e32 v[130:131], v[150:151]
	v_mov_b64_e32 v[132:133], v[148:149]
	v_mov_b64_e32 v[134:135], v[146:147]
	v_mov_b64_e32 v[150:151], v[168:169]
	v_mov_b64_e32 v[148:149], v[166:167]
	v_mov_b64_e32 v[146:147], v[164:165]
	s_cbranch_scc0 .LBB0_450

; #define GAS __attribute__((address_space(1)))
; DI unsigned pk2(float lo, float hi) { f32x2_t v = {lo, hi}; bf16x2_t b = __builtin_convertvector(v, bf16x2_t); return __builtin_bit_cast(unsigned, b); }
; DI float bflo(unsigned w) { return __uint_as_float(w << 16); }
; DI float bfhi(unsigned w) { return __uint_as_float(w & 0xffff0000u); }
; DI void phase_e(const Ctx& C, int nslab, int has_post, int pl, int ps, float pw, int has_pre, int ql, int qs, int nrows,
;                 const GAS float* xsrc, const GAS float* csrc, GAS float* xdst, GAS float* cdst, bool xs16, bool xd16) {
;     ...
;         if (has_post) {
;             f32x4 y[4]; float ss = 0.f;
; #pragma unroll
;             for (int j = 0; j < 4; ++j) {
;                 if (isx || nslab == 0) { y[j] = (f32x4){bflo(yw[j].x), bfhi(yw[j].x), bflo(yw[j].y), bfhi(yw[j].y)}; }
;                 else { y[j] = (f32x4){0.f, 0.f, 0.f, 0.f};
;                     for (int s = 0; s < nslab; ++s) { const u32x2 w = *(const GAS u32x2*)(YS + ((size_t)s * MC + (row - MX)) * 1024 + 256 * j + 4 * lane); y[j] += (f32x4){bflo(w.x), bfhi(w.x), bflo(w.y), bfhi(w.y)}; } }
;                 ss += (y[j][0] * y[j][0] + y[j][1] * y[j][1]) + (y[j][2] * y[j][2] + y[j][3] * y[j][3]); }
;             const float r = rsqrtf(wave_sum(ss) * (1.0f / 1024.0f) + EPS);
;             if (isx && xd16) { GAS bf16* d16 = (GAS bf16*)xdst + (size_t)row * 1024;
; #pragma unroll
;                 for (int j = 0; j < 4; ++j) { v[j] += pw * gt[j] * ((y[j] * r) * gpo[j]); u32x2 w; w.x = pk2(v[j][0], v[j][1]); w.y = pk2(v[j][2], v[j][3]); __builtin_nontemporal_store(w, (GAS u32x2*)(d16 + 256 * j + 4 * lane));
;                     v[j] = (f32x4){bflo(w.x), bfhi(w.x), bflo(w.y), bfhi(w.y)}; }
;             } else { GAS float* dst = isx ? xdst + (size_t)row * 1024 : cdst + (size_t)(row - MX) * 1024;
; #pragma unroll
;                 for (int j = 0; j < 4; ++j) { v[j] += pw * gt[j] * ((y[j] * r) * gpo[j]); __builtin_nontemporal_store(v[j], (GAS f32x4*)(dst + 256 * j + 4 * lane)); } }
.LBB0_446:
	v_mul_f32_e32 v130, v141, v141
	v_mul_f32_e32 v131, v139, v139
	v_fmac_f32_e32 v130, v140, v140
	v_fmac_f32_e32 v131, v138, v138
	v_add_f32_e32 v130, v130, v131
	v_mul_f32_e32 v131, v171, v171
	v_mul_f32_e32 v132, v173, v173
	v_fmac_f32_e32 v131, v170, v170
	v_fmac_f32_e32 v132, v172, v172
	v_add_f32_e32 v131, v131, v132
	v_add_f32_e32 v130, v130, v131
	v_mul_f32_e32 v131, v175, v175
	v_mul_f32_e32 v132, v177, v177
	v_fmac_f32_e32 v131, v174, v174
	v_fmac_f32_e32 v132, v176, v176
	v_add_f32_e32 v131, v131, v132
	v_add_f32_e32 v136, v130, v131
	v_pk_mul_f32 v[130:131], v[180:181], v[180:181]
	v_pk_mul_f32 v[132:133], v[178:179], v[178:179]
	s_and_b64 s[0:1], exec, s[0:1]
	v_pk_mov_b32 v[134:135], v[132:133], v[130:131] op_sel:[1,0]
	v_mov_b32_e32 v133, v131
	v_pk_add_f32 v[130:131], v[134:135], v[132:133]
	s_ashr_i32 s13, s12, 31
	v_add_f32_e32 v130, v130, v131
	v_add_f32_e32 v130, v136, v130
	s_nop 1
	v_add_f32_dpp v130, v130, v130 quad_perm:[1,0,3,2] row_mask:0xf bank_mask:0xf
	s_nop 1
	v_add_f32_dpp v130, v130, v130 quad_perm:[2,3,0,1] row_mask:0xf bank_mask:0xf
	s_nop 1
	v_add_f32_dpp v130, v130, v130 row_half_mirror row_mask:0xf bank_mask:0xf
	s_nop 1
	v_add_f32_dpp v130, v130, v130 row_mirror row_mask:0xf bank_mask:0xf
	s_nop 1
	v_add_f32_dpp v130, v130, v130 row_bcast:15 row_mask:0xa bank_mask:0xf
	s_nop 1
	v_add_f32_dpp v130, v130, v130 row_bcast:31 row_mask:0xc bank_mask:0xf
	s_nop 0
	v_readlane_b32 s64, v130, 63
	s_nop 1
	v_mov_b32_e32 v132, s64
	s_waitcnt lgkmcnt(0)
	s_mov_b64 s[22:23], -1
	s_waitcnt vmcnt(7)
	v_pk_mul_f32 v[188:189], v[98:99], 0.5 op_sel_hi:[1,0]
	s_waitcnt vmcnt(6)
	v_pk_mul_f32 v[186:187], v[102:103], 0.5 op_sel_hi:[1,0]
	s_waitcnt vmcnt(4)
	v_pk_mul_f32 v[184:185], v[106:107], 0.5 op_sel_hi:[1,0]
	v_pk_mul_f32 v[130:131], v[96:97], 0.5 op_sel_hi:[1,0]
	v_fmamk_f32 v132, v132, 0x3a800000, v197
	v_mul_f32_e32 v133, 0x4b800000, v132
	v_cmp_gt_f32_e32 vcc, s47, v132
	s_nop 1
	v_cndmask_b32_e32 v132, v132, v133, vcc
	v_rsq_f32_e32 v134, v132
	v_pk_mul_f32 v[132:133], v[94:95], 0.5 op_sel_hi:[1,0]
	v_mul_f32_e32 v135, 0x45800000, v134
	v_cndmask_b32_e32 v182, v134, v135, vcc
	v_mov_b32_e32 v183, v182
	v_pk_mul_f32 v[134:135], v[138:139], v[182:183] op_sel_hi:[1,0]
	v_pk_mul_f32 v[136:137], v[140:141], v[182:183] op_sel_hi:[1,0]
	v_pk_mul_f32 v[134:135], v[4:5], v[134:135]
	v_pk_mul_f32 v[136:137], v[2:3], v[136:137]
	v_pk_fma_f32 v[128:129], v[130:131], v[134:135], v[128:129]
	v_pk_fma_f32 v[126:127], v[132:133], v[136:137], v[126:127]
	s_mov_b64 vcc, s[0:1]
	s_cbranch_vccz .LBB0_448
	v_mov_b32_e32 v138, v182
	v_mov_b32_e32 v139, v182
	v_pk_mul_f32 v[132:133], v[172:173], v[138:139]
	v_pk_mul_f32 v[134:135], v[170:171], v[182:183]
	v_pk_mul_f32 v[130:131], v[100:101], 0.5 op_sel_hi:[1,0]
	v_pk_mul_f32 v[132:133], v[8:9], v[132:133]
	v_pk_mul_f32 v[134:135], v[6:7], v[134:135]
	v_pk_mul_f32 v[136:137], v[176:177], v[138:139]
	v_pk_mul_f32 v[140:141], v[174:175], v[182:183]
	v_pk_fma_f32 v[132:133], v[130:131], v[132:133], v[60:61]
	v_pk_fma_f32 v[130:131], v[188:189], v[134:135], v[58:59]
	v_pk_mul_f32 v[134:135], v[104:105], 0.5 op_sel_hi:[1,0]
	v_pk_mul_f32 v[136:137], v[20:21], v[136:137]
	v_pk_mul_f32 v[140:141], v[18:19], v[140:141]
	v_pk_mul_f32 v[138:139], v[180:181], v[138:139]
	v_pk_mul_f32 v[200:201], v[178:179], v[182:183]
	s_lshl_b64 s[0:1], s[6:7], 12
	v_pk_fma_f32 v[136:137], v[134:135], v[136:137], v[56:57]
	v_pk_fma_f32 v[134:135], v[186:187], v[140:141], v[54:55]
	v_pk_mul_f32 v[140:141], v[108:109], 0.5 op_sel_hi:[1,0]
	v_pk_mul_f32 v[138:139], v[24:25], v[138:139]
	v_pk_mul_f32 v[200:201], v[22:23], v[200:201]
	v_lshl_add_u64 v[198:199], v[160:161], 0, s[0:1]
	v_pk_fma_f32 v[140:141], v[140:141], v[138:139], v[52:53]
	v_pk_fma_f32 v[138:139], v[184:185], v[200:201], v[50:51]
	global_store_dwordx4 v[198:199], v[126:129], off nt
	global_store_dwordx4 v[198:199], v[130:133], off offset:1024 nt
	global_store_dwordx4 v[198:199], v[134:137], off offset:2048 nt
	global_store_dwordx4 v[198:199], v[138:141], off offset:3072 nt
	s_lshl_b64 s[2:3], s[12:13], 11
	s_mov_b64 s[22:23], 0

; #define GAS __attribute__((address_space(1)))
; DI unsigned pk2(float lo, float hi) { f32x2_t v = {lo, hi}; bf16x2_t b = __builtin_convertvector(v, bf16x2_t); return __builtin_bit_cast(unsigned, b); }
; DI float silu(float x) { return x * sigm(x); }
; DI void phase_conv(const Ctx& C) {
;     ...
;         const float mean = wave_sum((a0[0] + a0[1]) + (a0[2] + a0[3]) + (a1[0] + a1[1]) + (a1[2] + a1[3])) * (1.0f / 512.0f);
;         a0 -= mean; a1 -= mean;
;         const float var = wave_sum((a0[0] * a0[0] + a0[1] * a0[1]) + (a0[2] * a0[2] + a0[3] * a0[3]) + (a1[0] * a1[0] + a1[1] * a1[1]) + (a1[2] * a1[2] + a1[3] * a1[3])) * (1.0f / 512.0f);
;         const float r = rsqrtf(var + EPS);
;         a0 = a0 * r * lg0 + lb0; a1 = a1 * r * lg1 + lb1;
;         u32x4 o; o.x = pk2(silu(a0[0]), silu(a0[1])); o.y = pk2(silu(a0[2]), silu(a0[3])); o.z = pk2(silu(a1[0]), silu(a1[1])); o.w = pk2(silu(a1[2]), silu(a1[3]));
;         *(GAS u32x4*)(MIX + (size_t)row * 1024 + 512 + c0) = o;
.LBB0_615:
	v_mov_b32_e32 v26, v41
	v_mov_b32_e32 v27, v38
	v_mov_b32_e32 v28, v40
	v_mov_b32_e32 v29, v39
	v_pk_add_f32 v[26:27], v[26:27], v[28:29]
	v_mov_b32_e32 v28, v42
	v_mov_b32_e32 v29, v44
	v_mov_b32_e32 v30, v43
	v_mov_b32_e32 v31, v45
	v_pk_add_f32 v[28:29], v[28:29], v[30:31]
	v_add_f32_e32 v26, v26, v27
	v_add_f32_e32 v26, v29, v26
	v_add_f32_e32 v26, v28, v26
	s_nop 1
	v_add_f32_dpp v26, v26, v26 quad_perm:[1,0,3,2] row_mask:0xf bank_mask:0xf
	s_nop 1
	v_add_f32_dpp v26, v26, v26 quad_perm:[2,3,0,1] row_mask:0xf bank_mask:0xf
	s_nop 1
	v_add_f32_dpp v26, v26, v26 row_half_mirror row_mask:0xf bank_mask:0xf
	s_nop 1
	v_add_f32_dpp v26, v26, v26 row_mirror row_mask:0xf bank_mask:0xf
	s_nop 1
	v_add_f32_dpp v26, v26, v26 row_bcast:15 row_mask:0xa bank_mask:0xf
	s_nop 1
	v_add_f32_dpp v26, v26, v26 row_bcast:31 row_mask:0xc bank_mask:0xf
	s_nop 0
	v_readlane_b32 s64, v26, 63
	s_nop 1
	v_mov_b32_e32 v26, s64
	s_waitcnt lgkmcnt(0)
	s_ashr_i32 s3, s2, 31
	s_lshl_b64 s[0:1], s[2:3], 11
	s_add_i32 s2, s2, 8
	s_cmp_ge_i32 s2, s4
	v_fmamk_f32 v41, v26, 0xbb000000, v41
	v_fmac_f32_e32 v40, 0xbb000000, v26
	v_fmamk_f32 v39, v26, 0xbb000000, v39
	v_fmac_f32_e32 v38, 0xbb000000, v26
	v_fmamk_f32 v45, v26, 0xbb000000, v45
	v_fmac_f32_e32 v44, 0xbb000000, v26
	v_fmamk_f32 v43, v26, 0xbb000000, v43
	v_fmac_f32_e32 v42, 0xbb000000, v26
	v_pk_mul_f32 v[26:27], v[38:39], v[38:39]
	v_pk_mul_f32 v[28:29], v[40:41], v[40:41]
	v_pk_mul_f32 v[30:31], v[42:43], v[42:43]
	v_pk_mul_f32 v[32:33], v[44:45], v[44:45]
	v_pk_mov_b32 v[54:55], v[28:29], v[26:27] op_sel:[1,0]
	v_mov_b32_e32 v29, v27
	v_mov_b32_e32 v26, v30
	v_mov_b32_e32 v27, v32
	v_mov_b32_e32 v32, v31
	v_pk_add_f32 v[28:29], v[54:55], v[28:29]
	v_pk_add_f32 v[26:27], v[26:27], v[32:33]
	v_add_f32_e32 v28, v28, v29
	v_add_f32_e32 v27, v27, v28
	v_add_f32_e32 v26, v26, v27
	s_nop 1
	v_add_f32_dpp v26, v26, v26 quad_perm:[1,0,3,2] row_mask:0xf bank_mask:0xf
	s_nop 1
	v_add_f32_dpp v26, v26, v26 quad_perm:[2,3,0,1] row_mask:0xf bank_mask:0xf
	s_nop 1
	v_add_f32_dpp v26, v26, v26 row_half_mirror row_mask:0xf bank_mask:0xf
	s_nop 1
	v_add_f32_dpp v26, v26, v26 row_mirror row_mask:0xf bank_mask:0xf
	s_nop 1
	v_add_f32_dpp v26, v26, v26 row_bcast:15 row_mask:0xa bank_mask:0xf
	s_nop 1
	v_add_f32_dpp v26, v26, v26 row_bcast:31 row_mask:0xc bank_mask:0xf
	s_nop 0
	v_readlane_b32 s64, v26, 63
	s_nop 1
	v_mov_b32_e32 v26, s64
	s_waitcnt lgkmcnt(0)
	v_fmamk_f32 v26, v26, 0x3b000000, v53
	v_mul_f32_e32 v27, 0x4b800000, v26
	v_cmp_gt_f32_e32 vcc, s8, v26
	s_nop 1
	v_cndmask_b32_e32 v26, v26, v27, vcc
	v_rsq_f32_e32 v26, v26
	s_nop 0
	v_mul_f32_e32 v27, 0x45800000, v26
	v_cndmask_b32_e32 v26, v26, v27, vcc
	v_pk_mul_f32 v[28:29], v[40:41], v[26:27] op_sel_hi:[1,0]
	v_pk_mul_f32 v[30:31], v[38:39], v[26:27] op_sel_hi:[1,0]
	v_pk_mul_f32 v[32:33], v[44:45], v[26:27] op_sel_hi:[1,0]
	v_pk_mul_f32 v[26:27], v[42:43], v[26:27] op_sel_hi:[1,0]
	v_pk_fma_f32 v[28:29], v[6:7], v[28:29], v[22:23]
	v_pk_fma_f32 v[38:39], v[12:13], v[26:27], v[16:17]
	v_mul_f32_e32 v26, 0xbfb8aa3b, v28
	v_mul_f32_e32 v27, 0xbfb8aa3b, v29
	v_exp_f32_e32 v26, v26
	v_exp_f32_e32 v27, v27
	v_pk_fma_f32 v[30:31], v[8:9], v[30:31], v[24:25]
	v_pk_fma_f32 v[32:33], v[10:11], v[32:33], v[14:15]
	v_mul_f32_e32 v40, 0xbfb8aa3b, v30
	v_mul_f32_e32 v41, 0xbfb8aa3b, v31
	v_add_f32_e32 v26, 1.0, v26
	v_add_f32_e32 v27, 1.0, v27
	v_mul_f32_e32 v42, 0xbfb8aa3b, v32
	v_mul_f32_e32 v43, 0xbfb8aa3b, v33
	v_mul_f32_e32 v44, 0xbfb8aa3b, v38
	v_mul_f32_e32 v45, 0xbfb8aa3b, v39
	v_exp_f32_e32 v40, v40
	v_exp_f32_e32 v41, v41
	v_rcp_f32_e32 v26, v26
	v_rcp_f32_e32 v27, v27
	v_exp_f32_e32 v42, v42
	v_exp_f32_e32 v43, v43
	v_exp_f32_e32 v44, v44
	v_exp_f32_e32 v45, v45
	v_add_f32_e32 v40, 1.0, v40
	v_add_f32_e32 v41, 1.0, v41
	v_pk_mul_f32 v[26:27], v[28:29], v[26:27]
	v_add_f32_e32 v42, 1.0, v42
	v_add_f32_e32 v43, 1.0, v43
	v_add_f32_e32 v44, 1.0, v44
	v_rcp_f32_e32 v40, v40
	v_rcp_f32_e32 v41, v41
	v_cvt_pk_bf16_f32 v26, v26, v27
	v_add_f32_e32 v27, 1.0, v45
	v_rcp_f32_e32 v42, v42
	v_rcp_f32_e32 v43, v43
	v_rcp_f32_e32 v44, v44
	v_rcp_f32_e32 v45, v27
	v_pk_mul_f32 v[28:29], v[30:31], v[40:41]
	v_pk_mul_f32 v[30:31], v[38:39], v[44:45]
	v_cvt_pk_bf16_f32 v27, v28, v29
	v_pk_mul_f32 v[28:29], v[32:33], v[42:43]
	s_nop 0
	v_cvt_pk_bf16_f32 v28, v28, v29
	v_cvt_pk_bf16_f32 v29, v30, v31
	v_lshl_add_u64 v[30:31], v[36:37], 0, s[0:1]
	global_store_dwordx4 v[30:31], v[26:29], off offset:1024
	s_cbranch_scc1 .LBB0_620

; #define GAS __attribute__((address_space(1)))
; DI unsigned pk2(float lo, float hi) { f32x2_t v = {lo, hi}; bf16x2_t b = __builtin_convertvector(v, bf16x2_t); return __builtin_bit_cast(unsigned, b); }
; DI void phase_e(const Ctx& C, int nslab, int has_post, int pl, int ps, float pw, int has_pre, int ql, int qs, int nrows,
;                 const GAS float* xsrc, const GAS float* csrc, GAS float* xdst, GAS float* cdst, bool xs16, bool xd16) {
;     ...
;         if (has_pre) {
;             float ss = 0.f;
; #pragma unroll
;             for (int j = 0; j < 4; ++j) ss += (v[j][0] * v[j][0] + v[j][1] * v[j][1]) + (v[j][2] * v[j][2] + v[j][3] * v[j][3]);
;             const float r = rsqrtf(wave_sum(ss) * (1.0f / 1024.0f) + EPS);
; #pragma unroll
;             for (int j = 0; j < 4; ++j) { const f32x4 h = ((v[j] * r) * gpr[j]) * (1.0f + sc[j]) + sh[j];
;                 u32x2 w; w.x = pk2(h[0], h[1]); w.y = pk2(h[2], h[3]); *(GAS u32x2*)(H + (size_t)row * 1024 + 256 * j + 4 * lane) = w; }
;         }
.LBB0_945:
	v_pk_mul_f32 v[54:55], v[80:81], v[80:81]
	v_pk_mul_f32 v[56:57], v[78:79], v[78:79]
	v_pk_mul_f32 v[46:47], v[132:133], v[132:133]
	v_pk_mul_f32 v[48:49], v[130:131], v[130:131]
	v_pk_mov_b32 v[58:59], v[56:57], v[54:55] op_sel:[1,0]
	v_mov_b32_e32 v57, v55
	v_pk_add_f32 v[54:55], v[58:59], v[56:57]
	v_pk_mov_b32 v[56:57], v[48:49], v[46:47] op_sel:[1,0]
	v_mov_b32_e32 v49, v47
	v_pk_add_f32 v[46:47], v[56:57], v[48:49]
	v_pk_add_f32 v[54:55], v[54:55], v[54:55] op_sel_hi:[0,1]
	v_pk_add_f32 v[46:47], v[46:47], v[46:47] op_sel_hi:[0,1]
	v_mul_f32_e32 v46, v134, v134
	v_pk_fma_f32 v[48:49], v[134:135], v[134:135], v[46:47] op_sel_hi:[1,1,0]
	v_mul_f32_e32 v46, v136, v136
	v_pk_fma_f32 v[56:57], v[136:137], v[136:137], v[46:47] op_sel_hi:[1,1,0]
	v_mul_f32_e32 v48, v138, v138
	v_mul_f32_e32 v56, v139, v139
	v_mul_f32_e32 v54, v140, v140
	v_mul_f32_e32 v46, v141, v141
	v_pk_add_f32 v[48:49], v[48:49], v[56:57]
	v_pk_add_f32 v[46:47], v[54:55], v[46:47]
	s_waitcnt vmcnt(10)
	v_pk_add_f32 v[54:55], v[66:67], 1.0 op_sel_hi:[1,0]
	v_pk_add_f32 v[46:47], v[48:49], v[46:47]
	v_pk_add_f32 v[48:49], v[68:69], 1.0 op_sel_hi:[1,0]
	v_add_f32_e32 v46, v46, v47
	s_nop 1
	v_add_f32_dpp v46, v46, v46 quad_perm:[1,0,3,2] row_mask:0xf bank_mask:0xf
	s_nop 1
	v_add_f32_dpp v46, v46, v46 quad_perm:[2,3,0,1] row_mask:0xf bank_mask:0xf
	s_nop 1
	v_add_f32_dpp v46, v46, v46 row_half_mirror row_mask:0xf bank_mask:0xf
	s_nop 1
	v_add_f32_dpp v46, v46, v46 row_mirror row_mask:0xf bank_mask:0xf
	s_nop 1
	v_add_f32_dpp v46, v46, v46 row_bcast:15 row_mask:0xa bank_mask:0xf
	s_nop 1
	v_add_f32_dpp v46, v46, v46 row_bcast:31 row_mask:0xc bank_mask:0xf
	s_nop 0
	v_readlane_b32 s64, v46, 63
	s_nop 1
	v_mov_b32_e32 v46, s64
	s_waitcnt lgkmcnt(0)
	s_add_i32 s0, s23, 8
	s_add_i32 s1, s23, -8
	s_cmp_lt_i32 s1, s17
	s_mov_b32 s23, s0
	v_fmamk_f32 v46, v46, 0x3a800000, v192
	v_mul_f32_e32 v47, 0x4b800000, v46
	v_cmp_gt_f32_e32 vcc, s27, v46
	s_nop 1
	v_cndmask_b32_e32 v46, v46, v47, vcc
	v_rsq_f32_e32 v56, v46
	v_lshl_add_u64 v[46:47], v[158:159], 0, s[2:3]
	v_mul_f32_e32 v57, 0x45800000, v56
	v_cndmask_b32_e32 v56, v56, v57, vcc
	v_pk_mul_f32 v[58:59], v[80:81], v[56:57] op_sel_hi:[1,0]
	v_pk_mul_f32 v[60:61], v[78:79], v[56:57] op_sel_hi:[1,0]
	v_pk_mul_f32 v[58:59], v[12:13], v[58:59]
	v_pk_mul_f32 v[60:61], v[10:11], v[60:61]
	s_waitcnt vmcnt(9)
	v_pk_fma_f32 v[48:49], v[48:49], v[58:59], v[72:73]
	v_pk_fma_f32 v[54:55], v[54:55], v[60:61], v[70:71]
	v_pk_mul_f32 v[78:79], v[132:133], v[56:57] op_sel_hi:[1,0]
	v_pk_mul_f32 v[80:81], v[130:131], v[56:57] op_sel_hi:[1,0]
	v_cvt_pk_bf16_f32 v54, v54, v55
	v_cvt_pk_bf16_f32 v55, v48, v49
	v_pk_mul_f32 v[80:81], v[14:15], v[80:81]
	global_store_dwordx2 v[46:47], v[54:55], off
	v_pk_mul_f32 v[48:49], v[16:17], v[78:79]
	s_waitcnt vmcnt(6)
	v_pk_add_f32 v[54:55], v[76:77], 1.0 op_sel_hi:[1,0]
	v_pk_add_f32 v[58:59], v[74:75], 1.0 op_sel_hi:[1,0]
	v_pk_fma_f32 v[48:49], v[54:55], v[48:49], v[84:85]
	v_pk_fma_f32 v[54:55], v[58:59], v[80:81], v[82:83]
	s_waitcnt vmcnt(4)
	v_pk_add_f32 v[58:59], v[88:89], 1.0 op_sel_hi:[1,0]
	v_cvt_pk_bf16_f32 v54, v54, v55
	v_cvt_pk_bf16_f32 v55, v48, v49
	global_store_dwordx2 v[46:47], v[54:55], off offset:512
	v_pk_mul_f32 v[48:49], v[136:137], v[56:57] op_sel_hi:[1,0]
	v_pk_mul_f32 v[54:55], v[134:135], v[56:57] op_sel_hi:[1,0]
	v_pk_mul_f32 v[48:49], v[28:29], v[48:49]
	v_pk_mul_f32 v[54:55], v[26:27], v[54:55]
	v_pk_add_f32 v[60:61], v[86:87], 1.0 op_sel_hi:[1,0]
	s_waitcnt vmcnt(3)
	v_pk_fma_f32 v[48:49], v[58:59], v[48:49], v[96:97]
	v_pk_fma_f32 v[54:55], v[60:61], v[54:55], v[94:95]
	v_pk_add_f32 v[58:59], v[62:63], 1.0 op_sel_hi:[1,0]
	v_cvt_pk_bf16_f32 v54, v54, v55
	v_cvt_pk_bf16_f32 v55, v48, v49
	global_store_dwordx2 v[46:47], v[54:55], off offset:1024
	v_pk_mul_f32 v[48:49], v[140:141], v[56:57] op_sel_hi:[1,0]
	v_pk_mul_f32 v[54:55], v[138:139], v[56:57] op_sel_hi:[1,0]
	v_pk_mul_f32 v[48:49], v[32:33], v[48:49]
	v_pk_mul_f32 v[54:55], v[30:31], v[54:55]
	v_pk_add_f32 v[56:57], v[64:65], 1.0 op_sel_hi:[1,0]
	s_waitcnt vmcnt(3)
	v_pk_fma_f32 v[54:55], v[58:59], v[54:55], v[90:91]
	v_pk_fma_f32 v[48:49], v[56:57], v[48:49], v[92:93]
	v_cvt_pk_bf16_f32 v54, v54, v55
	v_cvt_pk_bf16_f32 v55, v48, v49
	global_store_dwordx2 v[46:47], v[54:55], off offset:1536
	s_mov_b64 vcc, s[98:99]
	s_cbranch_vccz .Leload_skip_0
	s_waitcnt vmcnt(8)
	v_lshlrev_b32_e32 v114, 16, v116
	v_and_b32_e32 v115, 0xffff0000, v116
	v_lshlrev_b32_e32 v116, 16, v117
	v_and_b32_e32 v117, 0xffff0000, v117
	v_lshlrev_b32_e32 v118, 16, v120
	v_and_b32_e32 v119, 0xffff0000, v120
	v_lshlrev_b32_e32 v120, 16, v121
	v_and_b32_e32 v121, 0xffff0000, v121
	v_lshlrev_b32_e32 v122, 16, v124
	v_and_b32_e32 v123, 0xffff0000, v124
	v_lshlrev_b32_e32 v124, 16, v125
	v_and_b32_e32 v125, 0xffff0000, v125
	v_lshlrev_b32_e32 v126, 16, v128
	v_and_b32_e32 v127, 0xffff0000, v128
	v_lshlrev_b32_e32 v128, 16, v129
	v_and_b32_e32 v129, 0xffff0000, v129

; #define GAS __attribute__((address_space(1)))
; DI unsigned pk2(float lo, float hi) { f32x2_t v = {lo, hi}; bf16x2_t b = __builtin_convertvector(v, bf16x2_t); return __builtin_bit_cast(unsigned, b); }
; DI float bflo(unsigned w) { return __uint_as_float(w << 16); }
; DI float bfhi(unsigned w) { return __uint_as_float(w & 0xffff0000u); }
; DI void phase_e(const Ctx& C, int nslab, int has_post, int pl, int ps, float pw, int has_pre, int ql, int qs, int nrows,
;                 const GAS float* xsrc, const GAS float* csrc, GAS float* xdst, GAS float* cdst, bool xs16, bool xd16) {
;     ...
;         if (has_post) {
;             f32x4 y[4]; float ss = 0.f;
; #pragma unroll
;             for (int j = 0; j < 4; ++j) {
;                 if (isx || nslab == 0) { y[j] = (f32x4){bflo(yw[j].x), bfhi(yw[j].x), bflo(yw[j].y), bfhi(yw[j].y)}; }
;                 else { y[j] = (f32x4){0.f, 0.f, 0.f, 0.f};
;                     for (int s = 0; s < nslab; ++s) { const u32x2 w = *(const GAS u32x2*)(YS + ((size_t)s * MC + (row - MX)) * 1024 + 256 * j + 4 * lane); y[j] += (f32x4){bflo(w.x), bfhi(w.x), bflo(w.y), bfhi(w.y)}; } }
;                 ss += (y[j][0] * y[j][0] + y[j][1] * y[j][1]) + (y[j][2] * y[j][2] + y[j][3] * y[j][3]); }
;             const float r = rsqrtf(wave_sum(ss) * (1.0f / 1024.0f) + EPS);
;             if (isx && xd16) { GAS bf16* d16 = (GAS bf16*)xdst + (size_t)row * 1024;
; #pragma unroll
;                 for (int j = 0; j < 4; ++j) { v[j] += pw * gt[j] * ((y[j] * r) * gpo[j]); u32x2 w; w.x = pk2(v[j][0], v[j][1]); w.y = pk2(v[j][2], v[j][3]); __builtin_nontemporal_store(w, (GAS u32x2*)(d16 + 256 * j + 4 * lane));
;                     v[j] = (f32x4){bflo(w.x), bfhi(w.x), bflo(w.y), bfhi(w.y)}; }
;             } else { GAS float* dst = isx ? xdst + (size_t)row * 1024 : cdst + (size_t)(row - MX) * 1024;
; #pragma unroll
;                 for (int j = 0; j < 4; ++j) { v[j] += pw * gt[j] * ((y[j] * r) * gpo[j]); __builtin_nontemporal_store(v[j], (GAS f32x4*)(dst + 256 * j + 4 * lane)); } }
.LBB0_971:
	v_mul_f32_e32 v130, v175, v175
	v_mul_f32_e32 v131, v139, v139
	v_fmac_f32_e32 v130, v174, v174
	v_fmac_f32_e32 v131, v138, v138
	v_add_f32_e32 v130, v130, v131
	v_mul_f32_e32 v131, v171, v171
	v_mul_f32_e32 v132, v173, v173
	v_fmac_f32_e32 v131, v170, v170
	v_fmac_f32_e32 v132, v172, v172
	v_add_f32_e32 v131, v131, v132
	v_add_f32_e32 v130, v130, v131
	v_mul_f32_e32 v131, v177, v177
	v_mul_f32_e32 v132, v179, v179
	v_fmac_f32_e32 v131, v176, v176
	v_fmac_f32_e32 v132, v178, v178
	v_add_f32_e32 v131, v131, v132
	v_add_f32_e32 v136, v130, v131
	v_pk_mul_f32 v[130:131], v[182:183], v[182:183]
	v_pk_mul_f32 v[132:133], v[180:181], v[180:181]
	s_and_b64 s[0:1], exec, s[0:1]
	v_pk_mov_b32 v[134:135], v[132:133], v[130:131] op_sel:[1,0]
	v_mov_b32_e32 v133, v131
	v_pk_add_f32 v[130:131], v[134:135], v[132:133]
	s_ashr_i32 s11, s10, 31
	v_add_f32_e32 v130, v130, v131
	v_add_f32_e32 v130, v136, v130
	s_nop 1
	v_add_f32_dpp v130, v130, v130 quad_perm:[1,0,3,2] row_mask:0xf bank_mask:0xf
	s_nop 1
	v_add_f32_dpp v130, v130, v130 quad_perm:[2,3,0,1] row_mask:0xf bank_mask:0xf
	s_nop 1
	v_add_f32_dpp v130, v130, v130 row_half_mirror row_mask:0xf bank_mask:0xf
	s_nop 1
	v_add_f32_dpp v130, v130, v130 row_mirror row_mask:0xf bank_mask:0xf
	s_nop 1
	v_add_f32_dpp v130, v130, v130 row_bcast:15 row_mask:0xa bank_mask:0xf
	s_nop 1
	v_add_f32_dpp v130, v130, v130 row_bcast:31 row_mask:0xc bank_mask:0xf
	s_nop 0
	v_readlane_b32 s64, v130, 63
	s_nop 1
	v_mov_b32_e32 v130, s64
	s_waitcnt lgkmcnt(0)
	s_mov_b64 s[12:13], -1
	v_fmamk_f32 v130, v130, 0x3a800000, v192
	v_mul_f32_e32 v131, 0x4b800000, v130
	v_cmp_gt_f32_e32 vcc, s27, v130
	s_nop 1
	v_cndmask_b32_e32 v130, v130, v131, vcc
	v_rsq_f32_e32 v130, v130
	s_nop 0
	v_mul_f32_e32 v131, 0x45800000, v130
	v_cndmask_b32_e32 v184, v130, v131, vcc
	v_mov_b32_e32 v185, v184
	v_pk_mul_f32 v[130:131], v[138:139], v[184:185] op_sel_hi:[1,0]
	v_pk_mul_f32 v[134:135], v[174:175], v[184:185] op_sel_hi:[1,0]
	v_pk_mul_f32 v[130:131], v[4:5], v[130:131]
	v_pk_mul_f32 v[134:135], v[2:3], v[134:135]
	s_waitcnt vmcnt(11)
	v_pk_fma_f32 v[80:81], v[100:101], v[130:131], v[80:81]
	v_pk_fma_f32 v[78:79], v[98:99], v[134:135], v[78:79]
	s_mov_b64 vcc, s[0:1]
	s_cbranch_vccz .LBB0_973
	v_mov_b32_e32 v138, v184
	v_mov_b32_e32 v139, v184
	v_pk_mul_f32 v[130:131], v[172:173], v[138:139]
	v_pk_mul_f32 v[132:133], v[170:171], v[184:185]
	v_pk_mul_f32 v[130:131], v[8:9], v[130:131]
	v_pk_mul_f32 v[134:135], v[6:7], v[132:133]
	s_waitcnt vmcnt(7)
	v_pk_fma_f32 v[132:133], v[104:105], v[130:131], v[60:61]
	v_pk_fma_f32 v[130:131], v[102:103], v[134:135], v[58:59]
	v_pk_mul_f32 v[134:135], v[178:179], v[138:139]
	v_pk_mul_f32 v[136:137], v[176:177], v[184:185]
	v_pk_mul_f32 v[134:135], v[20:21], v[134:135]
	v_pk_mul_f32 v[140:141], v[18:19], v[136:137]
	s_waitcnt vmcnt(6)
	v_pk_fma_f32 v[136:137], v[108:109], v[134:135], v[56:57]
	v_pk_fma_f32 v[134:135], v[106:107], v[140:141], v[54:55]
	v_pk_mul_f32 v[138:139], v[182:183], v[138:139]
	v_pk_mul_f32 v[140:141], v[180:181], v[184:185]
	s_lshl_b64 s[0:1], s[4:5], 12
	v_pk_mul_f32 v[138:139], v[24:25], v[138:139]
	v_pk_mul_f32 v[194:195], v[22:23], v[140:141]
	v_lshl_add_u64 v[174:175], v[160:161], 0, s[0:1]
	s_waitcnt vmcnt(4)
	v_pk_fma_f32 v[140:141], v[112:113], v[138:139], v[48:49]
	v_pk_fma_f32 v[138:139], v[110:111], v[194:195], v[46:47]
	global_store_dwordx4 v[174:175], v[78:81], off nt
	global_store_dwordx4 v[174:175], v[130:133], off offset:1024 nt
	global_store_dwordx4 v[174:175], v[134:137], off offset:2048 nt
	global_store_dwordx4 v[174:175], v[138:141], off offset:3072 nt
	s_lshl_b64 s[2:3], s[10:11], 11
	s_mov_b64 s[12:13], 0

; #define GAS __attribute__((address_space(1)))
; DI unsigned pk2(float lo, float hi) { f32x2_t v = {lo, hi}; bf16x2_t b = __builtin_convertvector(v, bf16x2_t); return __builtin_bit_cast(unsigned, b); }
; DI void phase_e(const Ctx& C, int nslab, int has_post, int pl, int ps, float pw, int has_pre, int ql, int qs, int nrows,
;                 const GAS float* xsrc, const GAS float* csrc, GAS float* xdst, GAS float* cdst, bool xs16, bool xd16) {
;     ...
;         if (has_pre) {
;             float ss = 0.f;
; #pragma unroll
;             for (int j = 0; j < 4; ++j) ss += (v[j][0] * v[j][0] + v[j][1] * v[j][1]) + (v[j][2] * v[j][2] + v[j][3] * v[j][3]);
;             const float r = rsqrtf(wave_sum(ss) * (1.0f / 1024.0f) + EPS);
; #pragma unroll
;             for (int j = 0; j < 4; ++j) { const f32x4 h = ((v[j] * r) * gpr[j]) * (1.0f + sc[j]) + sh[j];
;                 u32x2 w; w.x = pk2(h[0], h[1]); w.y = pk2(h[2], h[3]); *(GAS u32x2*)(H + (size_t)row * 1024 + 256 * j + 4 * lane) = w; }
;         }
.LBB0_1212:
	v_pk_mul_f32 v[54:55], v[100:101], v[100:101]
	v_pk_mul_f32 v[56:57], v[98:99], v[98:99]
	v_pk_mul_f32 v[46:47], v[132:133], v[132:133]
	v_pk_mul_f32 v[48:49], v[130:131], v[130:131]
	v_pk_mov_b32 v[58:59], v[56:57], v[54:55] op_sel:[1,0]
	v_mov_b32_e32 v57, v55
	v_pk_add_f32 v[54:55], v[58:59], v[56:57]
	v_pk_mov_b32 v[56:57], v[48:49], v[46:47] op_sel:[1,0]
	v_mov_b32_e32 v49, v47
	v_pk_add_f32 v[46:47], v[56:57], v[48:49]
	v_pk_add_f32 v[54:55], v[54:55], v[54:55] op_sel_hi:[0,1]
	v_pk_add_f32 v[46:47], v[46:47], v[46:47] op_sel_hi:[0,1]
	v_mul_f32_e32 v46, v134, v134
	v_pk_fma_f32 v[48:49], v[134:135], v[134:135], v[46:47] op_sel_hi:[1,1,0]
	v_mul_f32_e32 v46, v136, v136
	v_pk_fma_f32 v[56:57], v[136:137], v[136:137], v[46:47] op_sel_hi:[1,1,0]
	v_mul_f32_e32 v48, v138, v138
	v_mul_f32_e32 v56, v139, v139
	v_mul_f32_e32 v54, v140, v140
	v_mul_f32_e32 v46, v141, v141
	v_pk_add_f32 v[48:49], v[48:49], v[56:57]
	v_pk_add_f32 v[46:47], v[54:55], v[46:47]
	v_pk_add_f32 v[54:55], v[66:67], 1.0 op_sel_hi:[1,0]
	v_pk_add_f32 v[46:47], v[48:49], v[46:47]
	v_pk_add_f32 v[48:49], v[68:69], 1.0 op_sel_hi:[1,0]
	v_add_f32_e32 v46, v46, v47
	s_nop 1
	v_add_f32_dpp v46, v46, v46 quad_perm:[1,0,3,2] row_mask:0xf bank_mask:0xf
	s_nop 1
	v_add_f32_dpp v46, v46, v46 quad_perm:[2,3,0,1] row_mask:0xf bank_mask:0xf
	s_nop 1
	v_add_f32_dpp v46, v46, v46 row_half_mirror row_mask:0xf bank_mask:0xf
	s_nop 1
	v_add_f32_dpp v46, v46, v46 row_mirror row_mask:0xf bank_mask:0xf
	s_nop 1
	v_add_f32_dpp v46, v46, v46 row_bcast:15 row_mask:0xa bank_mask:0xf
	s_nop 1
	v_add_f32_dpp v46, v46, v46 row_bcast:31 row_mask:0xc bank_mask:0xf
	s_nop 0
	v_readlane_b32 s64, v46, 63
	s_nop 1
	v_mov_b32_e32 v46, s64
	s_waitcnt lgkmcnt(0)
	s_add_i32 s0, s22, 8
	s_add_i32 s1, s22, -8
	s_cmp_lt_i32 s1, s17
	s_mov_b32 s22, s0
	v_mov_b64_e32 v[170:171], v[144:145]
	s_waitcnt vmcnt(3)
	v_mov_b64_e32 v[144:145], v[162:163]
	v_fmamk_f32 v46, v46, 0x3a800000, v196
	v_mul_f32_e32 v47, 0x4b800000, v46
	v_cmp_gt_f32_e32 vcc, s25, v46
	s_nop 1
	v_cndmask_b32_e32 v46, v46, v47, vcc
	v_rsq_f32_e32 v56, v46
	v_lshl_add_u64 v[46:47], v[158:159], 0, s[2:3]
	v_mul_f32_e32 v57, 0x45800000, v56
	v_cndmask_b32_e32 v56, v56, v57, vcc
	v_pk_mul_f32 v[58:59], v[100:101], v[56:57] op_sel_hi:[1,0]
	v_pk_mul_f32 v[60:61], v[98:99], v[56:57] op_sel_hi:[1,0]
	v_pk_mul_f32 v[58:59], v[12:13], v[58:59]
	v_pk_mul_f32 v[60:61], v[10:11], v[60:61]
	v_pk_fma_f32 v[48:49], v[48:49], v[58:59], v[72:73]
	v_pk_fma_f32 v[54:55], v[54:55], v[60:61], v[70:71]
	v_pk_mul_f32 v[98:99], v[132:133], v[56:57] op_sel_hi:[1,0]
	v_pk_mul_f32 v[100:101], v[130:131], v[56:57] op_sel_hi:[1,0]
	v_cvt_pk_bf16_f32 v54, v54, v55
	v_cvt_pk_bf16_f32 v55, v48, v49
	v_pk_mul_f32 v[100:101], v[14:15], v[100:101]
	global_store_dwordx2 v[46:47], v[54:55], off
	v_pk_mul_f32 v[48:49], v[16:17], v[98:99]
	v_pk_add_f32 v[54:55], v[76:77], 1.0 op_sel_hi:[1,0]
	v_pk_add_f32 v[58:59], v[74:75], 1.0 op_sel_hi:[1,0]
	v_pk_fma_f32 v[48:49], v[54:55], v[48:49], v[80:81]
	v_pk_fma_f32 v[54:55], v[58:59], v[100:101], v[78:79]
	v_pk_add_f32 v[58:59], v[84:85], 1.0 op_sel_hi:[1,0]
	v_cvt_pk_bf16_f32 v54, v54, v55
	v_cvt_pk_bf16_f32 v55, v48, v49
	global_store_dwordx2 v[46:47], v[54:55], off offset:512
	v_pk_mul_f32 v[48:49], v[136:137], v[56:57] op_sel_hi:[1,0]
	v_pk_mul_f32 v[54:55], v[134:135], v[56:57] op_sel_hi:[1,0]
	v_pk_mul_f32 v[48:49], v[28:29], v[48:49]
	v_pk_mul_f32 v[54:55], v[26:27], v[54:55]
	v_pk_add_f32 v[60:61], v[82:83], 1.0 op_sel_hi:[1,0]
	s_waitcnt vmcnt(3)
	v_pk_fma_f32 v[48:49], v[58:59], v[48:49], v[92:93]
	v_pk_fma_f32 v[54:55], v[60:61], v[54:55], v[90:91]
	v_pk_add_f32 v[58:59], v[62:63], 1.0 op_sel_hi:[1,0]
	v_cvt_pk_bf16_f32 v54, v54, v55
	v_cvt_pk_bf16_f32 v55, v48, v49
	global_store_dwordx2 v[46:47], v[54:55], off offset:1024
	v_pk_mul_f32 v[48:49], v[140:141], v[56:57] op_sel_hi:[1,0]
	v_pk_mul_f32 v[54:55], v[138:139], v[56:57] op_sel_hi:[1,0]
	v_pk_mul_f32 v[48:49], v[32:33], v[48:49]
	v_pk_mul_f32 v[54:55], v[30:31], v[54:55]
	v_pk_add_f32 v[56:57], v[64:65], 1.0 op_sel_hi:[1,0]
	s_waitcnt vmcnt(3)
	v_pk_fma_f32 v[54:55], v[58:59], v[54:55], v[86:87]
	v_pk_fma_f32 v[48:49], v[56:57], v[48:49], v[88:89]
	v_cvt_pk_bf16_f32 v54, v54, v55
	v_cvt_pk_bf16_f32 v55, v48, v49
	global_store_dwordx2 v[46:47], v[54:55], off offset:1536
	s_mov_b64 vcc, s[98:99]
	s_cbranch_vccz .Leload_skip_1
	s_waitcnt vmcnt(8)
	v_lshlrev_b32_e32 v114, 16, v116
	v_and_b32_e32 v115, 0xffff0000, v116
	v_lshlrev_b32_e32 v116, 16, v117
	v_and_b32_e32 v117, 0xffff0000, v117
	v_lshlrev_b32_e32 v118, 16, v120
	v_and_b32_e32 v119, 0xffff0000, v120
	v_lshlrev_b32_e32 v120, 16, v121
	v_and_b32_e32 v121, 0xffff0000, v121
	v_lshlrev_b32_e32 v122, 16, v124
	v_and_b32_e32 v123, 0xffff0000, v124
	v_lshlrev_b32_e32 v124, 16, v125
	v_and_b32_e32 v125, 0xffff0000, v125
	v_lshlrev_b32_e32 v126, 16, v128
	v_and_b32_e32 v127, 0xffff0000, v128
	v_lshlrev_b32_e32 v128, 16, v129
	v_and_b32_e32 v129, 0xffff0000, v129

; #define GAS __attribute__((address_space(1)))
; DI unsigned pk2(float lo, float hi) { f32x2_t v = {lo, hi}; bf16x2_t b = __builtin_convertvector(v, bf16x2_t); return __builtin_bit_cast(unsigned, b); }
; DI float bflo(unsigned w) { return __uint_as_float(w << 16); }
; DI float bfhi(unsigned w) { return __uint_as_float(w & 0xffff0000u); }
; DI void phase_e(const Ctx& C, int nslab, int has_post, int pl, int ps, float pw, int has_pre, int ql, int qs, int nrows,
;                 const GAS float* xsrc, const GAS float* csrc, GAS float* xdst, GAS float* cdst, bool xs16, bool xd16) {
;     ...
;         if (has_post) {
;             f32x4 y[4]; float ss = 0.f;
; #pragma unroll
;             for (int j = 0; j < 4; ++j) {
;                 if (isx || nslab == 0) { y[j] = (f32x4){bflo(yw[j].x), bfhi(yw[j].x), bflo(yw[j].y), bfhi(yw[j].y)}; }
;                 else { y[j] = (f32x4){0.f, 0.f, 0.f, 0.f};
;                     for (int s = 0; s < nslab; ++s) { const u32x2 w = *(const GAS u32x2*)(YS + ((size_t)s * MC + (row - MX)) * 1024 + 256 * j + 4 * lane); y[j] += (f32x4){bflo(w.x), bfhi(w.x), bflo(w.y), bfhi(w.y)}; } }
;                 ss += (y[j][0] * y[j][0] + y[j][1] * y[j][1]) + (y[j][2] * y[j][2] + y[j][3] * y[j][3]); }
;             const float r = rsqrtf(wave_sum(ss) * (1.0f / 1024.0f) + EPS);
;             if (isx && xd16) { GAS bf16* d16 = (GAS bf16*)xdst + (size_t)row * 1024;
; #pragma unroll
;                 for (int j = 0; j < 4; ++j) { v[j] += pw * gt[j] * ((y[j] * r) * gpo[j]); u32x2 w; w.x = pk2(v[j][0], v[j][1]); w.y = pk2(v[j][2], v[j][3]); __builtin_nontemporal_store(w, (GAS u32x2*)(d16 + 256 * j + 4 * lane));
;                     v[j] = (f32x4){bflo(w.x), bfhi(w.x), bflo(w.y), bfhi(w.y)}; }
;             } else { GAS float* dst = isx ? xdst + (size_t)row * 1024 : cdst + (size_t)(row - MX) * 1024;
; #pragma unroll
;                 for (int j = 0; j < 4; ++j) { v[j] += pw * gt[j] * ((y[j] * r) * gpo[j]); __builtin_nontemporal_store(v[j], (GAS f32x4*)(dst + 256 * j + 4 * lane)); } }
.LBB0_1238:
	v_mul_f32_e32 v130, v141, v141
	v_mul_f32_e32 v131, v139, v139
	v_fmac_f32_e32 v130, v140, v140
	v_fmac_f32_e32 v131, v138, v138
	v_add_f32_e32 v130, v130, v131
	v_mul_f32_e32 v131, v171, v171
	v_mul_f32_e32 v132, v173, v173
	v_fmac_f32_e32 v131, v170, v170
	v_fmac_f32_e32 v132, v172, v172
	v_add_f32_e32 v131, v131, v132
	v_add_f32_e32 v130, v130, v131
	v_mul_f32_e32 v131, v175, v175
	v_mul_f32_e32 v132, v177, v177
	v_fmac_f32_e32 v131, v174, v174
	v_fmac_f32_e32 v132, v176, v176
	v_add_f32_e32 v131, v131, v132
	v_add_f32_e32 v136, v130, v131
	v_pk_mul_f32 v[130:131], v[180:181], v[180:181]
	v_pk_mul_f32 v[132:133], v[178:179], v[178:179]
	s_and_b64 s[0:1], exec, s[0:1]
	v_pk_mov_b32 v[134:135], v[132:133], v[130:131] op_sel:[1,0]
	v_mov_b32_e32 v133, v131
	v_pk_add_f32 v[130:131], v[134:135], v[132:133]
	s_ashr_i32 s11, s10, 31
	v_add_f32_e32 v130, v130, v131
	v_add_f32_e32 v130, v136, v130
	s_nop 1
	v_add_f32_dpp v130, v130, v130 quad_perm:[1,0,3,2] row_mask:0xf bank_mask:0xf
	s_nop 1
	v_add_f32_dpp v130, v130, v130 quad_perm:[2,3,0,1] row_mask:0xf bank_mask:0xf
	s_nop 1
	v_add_f32_dpp v130, v130, v130 row_half_mirror row_mask:0xf bank_mask:0xf
	s_nop 1
	v_add_f32_dpp v130, v130, v130 row_mirror row_mask:0xf bank_mask:0xf
	s_nop 1
	v_add_f32_dpp v130, v130, v130 row_bcast:15 row_mask:0xa bank_mask:0xf
	s_nop 1
	v_add_f32_dpp v130, v130, v130 row_bcast:31 row_mask:0xc bank_mask:0xf
	s_nop 0
	v_readlane_b32 s64, v130, 63
	s_nop 1
	v_mov_b32_e32 v132, s64
	s_waitcnt lgkmcnt(0)
	s_mov_b64 s[12:13], -1
	s_waitcnt vmcnt(7)
	v_pk_mul_f32 v[188:189], v[102:103], 0.5 op_sel_hi:[1,0]
	s_waitcnt vmcnt(6)
	v_pk_mul_f32 v[186:187], v[106:107], 0.5 op_sel_hi:[1,0]
	s_waitcnt vmcnt(4)
	v_pk_mul_f32 v[184:185], v[110:111], 0.5 op_sel_hi:[1,0]
	v_pk_mul_f32 v[130:131], v[96:97], 0.5 op_sel_hi:[1,0]
	v_fmamk_f32 v132, v132, 0x3a800000, v196
	v_mul_f32_e32 v133, 0x4b800000, v132
	v_cmp_gt_f32_e32 vcc, s25, v132
	s_nop 1
	v_cndmask_b32_e32 v132, v132, v133, vcc
	v_rsq_f32_e32 v134, v132
	v_pk_mul_f32 v[132:133], v[94:95], 0.5 op_sel_hi:[1,0]
	v_mul_f32_e32 v135, 0x45800000, v134
	v_cndmask_b32_e32 v182, v134, v135, vcc
	v_mov_b32_e32 v183, v182
	v_pk_mul_f32 v[134:135], v[138:139], v[182:183] op_sel_hi:[1,0]
	v_pk_mul_f32 v[136:137], v[140:141], v[182:183] op_sel_hi:[1,0]
	v_pk_mul_f32 v[134:135], v[4:5], v[134:135]
	v_pk_mul_f32 v[136:137], v[2:3], v[136:137]
	v_pk_fma_f32 v[100:101], v[130:131], v[134:135], v[100:101]
	v_pk_fma_f32 v[98:99], v[132:133], v[136:137], v[98:99]
	s_mov_b64 vcc, s[0:1]
	s_cbranch_vccz .LBB0_1240
	v_mov_b32_e32 v138, v182
	v_mov_b32_e32 v139, v182
	v_pk_mul_f32 v[132:133], v[172:173], v[138:139]
	v_pk_mul_f32 v[134:135], v[170:171], v[182:183]
	v_pk_mul_f32 v[130:131], v[104:105], 0.5 op_sel_hi:[1,0]
	v_pk_mul_f32 v[132:133], v[8:9], v[132:133]
	v_pk_mul_f32 v[134:135], v[6:7], v[134:135]
	v_pk_mul_f32 v[136:137], v[176:177], v[138:139]
	v_pk_mul_f32 v[140:141], v[174:175], v[182:183]
	v_pk_fma_f32 v[132:133], v[130:131], v[132:133], v[60:61]
	v_pk_fma_f32 v[130:131], v[188:189], v[134:135], v[58:59]
	v_pk_mul_f32 v[134:135], v[108:109], 0.5 op_sel_hi:[1,0]
	v_pk_mul_f32 v[136:137], v[20:21], v[136:137]
	v_pk_mul_f32 v[140:141], v[18:19], v[140:141]
	v_pk_mul_f32 v[138:139], v[180:181], v[138:139]
	v_pk_mul_f32 v[200:201], v[178:179], v[182:183]
	s_lshl_b64 s[0:1], s[4:5], 12
	v_pk_fma_f32 v[136:137], v[134:135], v[136:137], v[56:57]
	v_pk_fma_f32 v[134:135], v[186:187], v[140:141], v[54:55]
	v_pk_mul_f32 v[140:141], v[112:113], 0.5 op_sel_hi:[1,0]
	v_pk_mul_f32 v[138:139], v[24:25], v[138:139]
	v_pk_mul_f32 v[200:201], v[22:23], v[200:201]
	v_lshl_add_u64 v[198:199], v[160:161], 0, s[0:1]
	v_pk_fma_f32 v[140:141], v[140:141], v[138:139], v[48:49]
	v_pk_fma_f32 v[138:139], v[184:185], v[200:201], v[46:47]
	global_store_dwordx4 v[198:199], v[98:101], off nt
	global_store_dwordx4 v[198:199], v[130:133], off offset:1024 nt
	global_store_dwordx4 v[198:199], v[134:137], off offset:2048 nt
	global_store_dwordx4 v[198:199], v[138:141], off offset:3072 nt
	s_lshl_b64 s[2:3], s[10:11], 11
	s_mov_b64 s[12:13], 0

; #define GAS __attribute__((address_space(1)))
; DI unsigned pk2(float lo, float hi) { f32x2_t v = {lo, hi}; bf16x2_t b = __builtin_convertvector(v, bf16x2_t); return __builtin_bit_cast(unsigned, b); }
; DI void phase_e(const Ctx& C, int nslab, int has_post, int pl, int ps, float pw, int has_pre, int ql, int qs, int nrows,
;                 const GAS float* xsrc, const GAS float* csrc, GAS float* xdst, GAS float* cdst, bool xs16, bool xd16) {
;     ...
;         if (has_pre) {
;             float ss = 0.f;
; #pragma unroll
;             for (int j = 0; j < 4; ++j) ss += (v[j][0] * v[j][0] + v[j][1] * v[j][1]) + (v[j][2] * v[j][2] + v[j][3] * v[j][3]);
;             const float r = rsqrtf(wave_sum(ss) * (1.0f / 1024.0f) + EPS);
; #pragma unroll
;             for (int j = 0; j < 4; ++j) { const f32x4 h = ((v[j] * r) * gpr[j]) * (1.0f + sc[j]) + sh[j];
;                 u32x2 w; w.x = pk2(h[0], h[1]); w.y = pk2(h[2], h[3]); *(GAS u32x2*)(H + (size_t)row * 1024 + 256 * j + 4 * lane) = w; }
;         }
.LBB0_1480:
	v_pk_mul_f32 v[54:55], v[100:101], v[100:101]
	v_pk_mul_f32 v[56:57], v[98:99], v[98:99]
	v_pk_mul_f32 v[46:47], v[132:133], v[132:133]
	v_pk_mul_f32 v[48:49], v[130:131], v[130:131]
	v_pk_mov_b32 v[58:59], v[56:57], v[54:55] op_sel:[1,0]
	v_mov_b32_e32 v57, v55
	v_pk_add_f32 v[54:55], v[58:59], v[56:57]
	v_pk_mov_b32 v[56:57], v[48:49], v[46:47] op_sel:[1,0]
	v_mov_b32_e32 v49, v47
	v_pk_add_f32 v[46:47], v[56:57], v[48:49]
	v_pk_add_f32 v[54:55], v[54:55], v[54:55] op_sel_hi:[0,1]
	v_pk_add_f32 v[46:47], v[46:47], v[46:47] op_sel_hi:[0,1]
	v_mul_f32_e32 v46, v134, v134
	v_pk_fma_f32 v[48:49], v[134:135], v[134:135], v[46:47] op_sel_hi:[1,1,0]
	v_mul_f32_e32 v46, v136, v136
	v_pk_fma_f32 v[56:57], v[136:137], v[136:137], v[46:47] op_sel_hi:[1,1,0]
	v_mul_f32_e32 v48, v138, v138
	v_mul_f32_e32 v56, v139, v139
	v_mul_f32_e32 v54, v140, v140
	v_mul_f32_e32 v46, v141, v141
	v_pk_add_f32 v[48:49], v[48:49], v[56:57]
	v_pk_add_f32 v[46:47], v[54:55], v[46:47]
	v_pk_add_f32 v[54:55], v[66:67], 1.0 op_sel_hi:[1,0]
	v_pk_add_f32 v[46:47], v[48:49], v[46:47]
	v_pk_add_f32 v[48:49], v[68:69], 1.0 op_sel_hi:[1,0]
	v_add_f32_e32 v46, v46, v47
	s_nop 1
	v_add_f32_dpp v46, v46, v46 quad_perm:[1,0,3,2] row_mask:0xf bank_mask:0xf
	s_nop 1
	v_add_f32_dpp v46, v46, v46 quad_perm:[2,3,0,1] row_mask:0xf bank_mask:0xf
	s_nop 1
	v_add_f32_dpp v46, v46, v46 row_half_mirror row_mask:0xf bank_mask:0xf
	s_nop 1
	v_add_f32_dpp v46, v46, v46 row_mirror row_mask:0xf bank_mask:0xf
	s_nop 1
	v_add_f32_dpp v46, v46, v46 row_bcast:15 row_mask:0xa bank_mask:0xf
	s_nop 1
	v_add_f32_dpp v46, v46, v46 row_bcast:31 row_mask:0xc bank_mask:0xf
	s_nop 0
	v_readlane_b32 s64, v46, 63
	s_nop 1
	v_mov_b32_e32 v46, s64
	s_waitcnt lgkmcnt(0)
	s_add_i32 s0, s23, 8
	s_add_i32 s1, s23, -8
	s_cmp_lt_i32 s1, s17
	s_mov_b32 s23, s0
	v_mov_b64_e32 v[170:171], v[144:145]
	s_waitcnt vmcnt(3)
	v_mov_b64_e32 v[144:145], v[162:163]
	v_fmamk_f32 v46, v46, 0x3a800000, v196
	v_mul_f32_e32 v47, 0x4b800000, v46
	v_cmp_gt_f32_e32 vcc, s27, v46
	s_nop 1
	v_cndmask_b32_e32 v46, v46, v47, vcc
	v_rsq_f32_e32 v56, v46
	v_lshl_add_u64 v[46:47], v[158:159], 0, s[2:3]
	v_mul_f32_e32 v57, 0x45800000, v56
	v_cndmask_b32_e32 v56, v56, v57, vcc
	v_pk_mul_f32 v[58:59], v[100:101], v[56:57] op_sel_hi:[1,0]
	v_pk_mul_f32 v[60:61], v[98:99], v[56:57] op_sel_hi:[1,0]
	v_pk_mul_f32 v[58:59], v[12:13], v[58:59]
	v_pk_mul_f32 v[60:61], v[10:11], v[60:61]
	v_pk_fma_f32 v[48:49], v[48:49], v[58:59], v[72:73]
	v_pk_fma_f32 v[54:55], v[54:55], v[60:61], v[70:71]
	v_pk_mul_f32 v[98:99], v[132:133], v[56:57] op_sel_hi:[1,0]
	v_pk_mul_f32 v[100:101], v[130:131], v[56:57] op_sel_hi:[1,0]
	v_cvt_pk_bf16_f32 v54, v54, v55
	v_cvt_pk_bf16_f32 v55, v48, v49
	v_pk_mul_f32 v[100:101], v[14:15], v[100:101]
	global_store_dwordx2 v[46:47], v[54:55], off
	v_pk_mul_f32 v[48:49], v[16:17], v[98:99]
	v_pk_add_f32 v[54:55], v[76:77], 1.0 op_sel_hi:[1,0]
	v_pk_add_f32 v[58:59], v[74:75], 1.0 op_sel_hi:[1,0]
	v_pk_fma_f32 v[48:49], v[54:55], v[48:49], v[80:81]
	v_pk_fma_f32 v[54:55], v[58:59], v[100:101], v[78:79]
	v_pk_add_f32 v[58:59], v[84:85], 1.0 op_sel_hi:[1,0]
	v_cvt_pk_bf16_f32 v54, v54, v55
	v_cvt_pk_bf16_f32 v55, v48, v49
	global_store_dwordx2 v[46:47], v[54:55], off offset:512
	v_pk_mul_f32 v[48:49], v[136:137], v[56:57] op_sel_hi:[1,0]
	v_pk_mul_f32 v[54:55], v[134:135], v[56:57] op_sel_hi:[1,0]
	v_pk_mul_f32 v[48:49], v[28:29], v[48:49]
	v_pk_mul_f32 v[54:55], v[26:27], v[54:55]
	v_pk_add_f32 v[60:61], v[82:83], 1.0 op_sel_hi:[1,0]
	s_waitcnt vmcnt(3)
	v_pk_fma_f32 v[48:49], v[58:59], v[48:49], v[92:93]
	v_pk_fma_f32 v[54:55], v[60:61], v[54:55], v[90:91]
	v_pk_add_f32 v[58:59], v[62:63], 1.0 op_sel_hi:[1,0]
	v_cvt_pk_bf16_f32 v54, v54, v55
	v_cvt_pk_bf16_f32 v55, v48, v49
	global_store_dwordx2 v[46:47], v[54:55], off offset:1024
	v_pk_mul_f32 v[48:49], v[140:141], v[56:57] op_sel_hi:[1,0]
	v_pk_mul_f32 v[54:55], v[138:139], v[56:57] op_sel_hi:[1,0]
	v_pk_mul_f32 v[48:49], v[32:33], v[48:49]
	v_pk_mul_f32 v[54:55], v[30:31], v[54:55]
	v_pk_add_f32 v[56:57], v[64:65], 1.0 op_sel_hi:[1,0]
	s_waitcnt vmcnt(3)
	v_pk_fma_f32 v[54:55], v[58:59], v[54:55], v[86:87]
	v_pk_fma_f32 v[48:49], v[56:57], v[48:49], v[88:89]
	v_cvt_pk_bf16_f32 v54, v54, v55
	v_cvt_pk_bf16_f32 v55, v48, v49
	global_store_dwordx2 v[46:47], v[54:55], off offset:1536
	s_mov_b64 vcc, s[98:99]
	s_cbranch_vccz .Leload_skip_2
	s_waitcnt vmcnt(8)
	v_lshlrev_b32_e32 v114, 16, v116
	v_and_b32_e32 v115, 0xffff0000, v116
	v_lshlrev_b32_e32 v116, 16, v117
	v_and_b32_e32 v117, 0xffff0000, v117
	v_lshlrev_b32_e32 v118, 16, v120
	v_and_b32_e32 v119, 0xffff0000, v120
	v_lshlrev_b32_e32 v120, 16, v121
	v_and_b32_e32 v121, 0xffff0000, v121
	v_lshlrev_b32_e32 v122, 16, v124
	v_and_b32_e32 v123, 0xffff0000, v124
	v_lshlrev_b32_e32 v124, 16, v125
	v_and_b32_e32 v125, 0xffff0000, v125
	v_lshlrev_b32_e32 v126, 16, v128
	v_and_b32_e32 v127, 0xffff0000, v128
	v_lshlrev_b32_e32 v128, 16, v129
	v_and_b32_e32 v129, 0xffff0000, v129

; #define GAS __attribute__((address_space(1)))
; DI unsigned pk2(float lo, float hi) { f32x2_t v = {lo, hi}; bf16x2_t b = __builtin_convertvector(v, bf16x2_t); return __builtin_bit_cast(unsigned, b); }
; DI float bflo(unsigned w) { return __uint_as_float(w << 16); }
; DI float bfhi(unsigned w) { return __uint_as_float(w & 0xffff0000u); }
; DI void phase_e(const Ctx& C, int nslab, int has_post, int pl, int ps, float pw, int has_pre, int ql, int qs, int nrows,
;                 const GAS float* xsrc, const GAS float* csrc, GAS float* xdst, GAS float* cdst, bool xs16, bool xd16) {
;     ...
;         if (has_post) {
;             f32x4 y[4]; float ss = 0.f;
; #pragma unroll
;             for (int j = 0; j < 4; ++j) {
;                 if (isx || nslab == 0) { y[j] = (f32x4){bflo(yw[j].x), bfhi(yw[j].x), bflo(yw[j].y), bfhi(yw[j].y)}; }
;                 else { y[j] = (f32x4){0.f, 0.f, 0.f, 0.f};
;                     for (int s = 0; s < nslab; ++s) { const u32x2 w = *(const GAS u32x2*)(YS + ((size_t)s * MC + (row - MX)) * 1024 + 256 * j + 4 * lane); y[j] += (f32x4){bflo(w.x), bfhi(w.x), bflo(w.y), bfhi(w.y)}; } }
;                 ss += (y[j][0] * y[j][0] + y[j][1] * y[j][1]) + (y[j][2] * y[j][2] + y[j][3] * y[j][3]); }
;             const float r = rsqrtf(wave_sum(ss) * (1.0f / 1024.0f) + EPS);
;             if (isx && xd16) { GAS bf16* d16 = (GAS bf16*)xdst + (size_t)row * 1024;
; #pragma unroll
;                 for (int j = 0; j < 4; ++j) { v[j] += pw * gt[j] * ((y[j] * r) * gpo[j]); u32x2 w; w.x = pk2(v[j][0], v[j][1]); w.y = pk2(v[j][2], v[j][3]); __builtin_nontemporal_store(w, (GAS u32x2*)(d16 + 256 * j + 4 * lane));
;                     v[j] = (f32x4){bflo(w.x), bfhi(w.x), bflo(w.y), bfhi(w.y)}; }
;             } else { GAS float* dst = isx ? xdst + (size_t)row * 1024 : cdst + (size_t)(row - MX) * 1024;
; #pragma unroll
;                 for (int j = 0; j < 4; ++j) { v[j] += pw * gt[j] * ((y[j] * r) * gpo[j]); __builtin_nontemporal_store(v[j], (GAS f32x4*)(dst + 256 * j + 4 * lane)); } }
.LBB0_1506:
	v_mul_f32_e32 v130, v141, v141
	v_mul_f32_e32 v131, v139, v139
	v_fmac_f32_e32 v130, v140, v140
	v_fmac_f32_e32 v131, v138, v138
	v_add_f32_e32 v130, v130, v131
	v_mul_f32_e32 v131, v171, v171
	v_mul_f32_e32 v132, v173, v173
	v_fmac_f32_e32 v131, v170, v170
	v_fmac_f32_e32 v132, v172, v172
	v_add_f32_e32 v131, v131, v132
	v_add_f32_e32 v130, v130, v131
	v_mul_f32_e32 v131, v175, v175
	v_mul_f32_e32 v132, v177, v177
	v_fmac_f32_e32 v131, v174, v174
	v_fmac_f32_e32 v132, v176, v176
	v_add_f32_e32 v131, v131, v132
	v_add_f32_e32 v136, v130, v131
	v_pk_mul_f32 v[130:131], v[180:181], v[180:181]
	v_pk_mul_f32 v[132:133], v[178:179], v[178:179]
	s_and_b64 s[0:1], exec, s[0:1]
	v_pk_mov_b32 v[134:135], v[132:133], v[130:131] op_sel:[1,0]
	v_mov_b32_e32 v133, v131
	v_pk_add_f32 v[130:131], v[134:135], v[132:133]
	s_ashr_i32 s11, s10, 31
	v_add_f32_e32 v130, v130, v131
	v_add_f32_e32 v130, v136, v130
	s_nop 1
	v_add_f32_dpp v130, v130, v130 quad_perm:[1,0,3,2] row_mask:0xf bank_mask:0xf
	s_nop 1
	v_add_f32_dpp v130, v130, v130 quad_perm:[2,3,0,1] row_mask:0xf bank_mask:0xf
	s_nop 1
	v_add_f32_dpp v130, v130, v130 row_half_mirror row_mask:0xf bank_mask:0xf
	s_nop 1
	v_add_f32_dpp v130, v130, v130 row_mirror row_mask:0xf bank_mask:0xf
	s_nop 1
	v_add_f32_dpp v130, v130, v130 row_bcast:15 row_mask:0xa bank_mask:0xf
	s_nop 1
	v_add_f32_dpp v130, v130, v130 row_bcast:31 row_mask:0xc bank_mask:0xf
	s_nop 0
	v_readlane_b32 s64, v130, 63
	s_nop 1
	v_mov_b32_e32 v132, s64
	s_waitcnt lgkmcnt(0)
	s_mov_b64 s[12:13], -1
	s_waitcnt vmcnt(7)
	v_pk_mul_f32 v[188:189], v[102:103], 0.5 op_sel_hi:[1,0]
	s_waitcnt vmcnt(6)
	v_pk_mul_f32 v[186:187], v[106:107], 0.5 op_sel_hi:[1,0]
	s_waitcnt vmcnt(4)
	v_pk_mul_f32 v[184:185], v[110:111], 0.5 op_sel_hi:[1,0]
	v_pk_mul_f32 v[130:131], v[96:97], 0.5 op_sel_hi:[1,0]
	v_fmamk_f32 v132, v132, 0x3a800000, v196
	v_mul_f32_e32 v133, 0x4b800000, v132
	v_cmp_gt_f32_e32 vcc, s27, v132
	s_nop 1
	v_cndmask_b32_e32 v132, v132, v133, vcc
	v_rsq_f32_e32 v134, v132
	v_pk_mul_f32 v[132:133], v[94:95], 0.5 op_sel_hi:[1,0]
	v_mul_f32_e32 v135, 0x45800000, v134
	v_cndmask_b32_e32 v182, v134, v135, vcc
	v_mov_b32_e32 v183, v182
	v_pk_mul_f32 v[134:135], v[138:139], v[182:183] op_sel_hi:[1,0]
	v_pk_mul_f32 v[136:137], v[140:141], v[182:183] op_sel_hi:[1,0]
	v_pk_mul_f32 v[134:135], v[4:5], v[134:135]
	v_pk_mul_f32 v[136:137], v[2:3], v[136:137]
	v_pk_fma_f32 v[100:101], v[130:131], v[134:135], v[100:101]
	v_pk_fma_f32 v[98:99], v[132:133], v[136:137], v[98:99]
	s_mov_b64 vcc, s[0:1]
	s_cbranch_vccz .LBB0_1508
	v_mov_b32_e32 v138, v182
	v_mov_b32_e32 v139, v182
	v_pk_mul_f32 v[132:133], v[172:173], v[138:139]
	v_pk_mul_f32 v[134:135], v[170:171], v[182:183]
	v_pk_mul_f32 v[130:131], v[104:105], 0.5 op_sel_hi:[1,0]
	v_pk_mul_f32 v[132:133], v[8:9], v[132:133]
	v_pk_mul_f32 v[134:135], v[6:7], v[134:135]
	v_pk_mul_f32 v[136:137], v[176:177], v[138:139]
	v_pk_mul_f32 v[140:141], v[174:175], v[182:183]
	v_pk_fma_f32 v[132:133], v[130:131], v[132:133], v[60:61]
	v_pk_fma_f32 v[130:131], v[188:189], v[134:135], v[58:59]
	v_pk_mul_f32 v[134:135], v[108:109], 0.5 op_sel_hi:[1,0]
	v_pk_mul_f32 v[136:137], v[20:21], v[136:137]
	v_pk_mul_f32 v[140:141], v[18:19], v[140:141]
	v_pk_mul_f32 v[138:139], v[180:181], v[138:139]
	v_pk_mul_f32 v[200:201], v[178:179], v[182:183]
	s_lshl_b64 s[0:1], s[4:5], 12
	v_pk_fma_f32 v[136:137], v[134:135], v[136:137], v[56:57]
	v_pk_fma_f32 v[134:135], v[186:187], v[140:141], v[54:55]
	v_pk_mul_f32 v[140:141], v[112:113], 0.5 op_sel_hi:[1,0]
	v_pk_mul_f32 v[138:139], v[24:25], v[138:139]
	v_pk_mul_f32 v[200:201], v[22:23], v[200:201]
	v_lshl_add_u64 v[198:199], v[160:161], 0, s[0:1]
	v_pk_fma_f32 v[140:141], v[140:141], v[138:139], v[48:49]
	v_pk_fma_f32 v[138:139], v[184:185], v[200:201], v[46:47]
	global_store_dwordx4 v[198:199], v[98:101], off nt
	global_store_dwordx4 v[198:199], v[130:133], off offset:1024 nt
	global_store_dwordx4 v[198:199], v[134:137], off offset:2048 nt
	global_store_dwordx4 v[198:199], v[138:141], off offset:3072 nt
	s_lshl_b64 s[2:3], s[10:11], 11
	s_mov_b64 s[12:13], 0

; #define GAS __attribute__((address_space(1)))
; DI unsigned pk2(float lo, float hi) { f32x2_t v = {lo, hi}; bf16x2_t b = __builtin_convertvector(v, bf16x2_t); return __builtin_bit_cast(unsigned, b); }
; DI void phase_e(const Ctx& C, int nslab, int has_post, int pl, int ps, float pw, int has_pre, int ql, int qs, int nrows,
;                 const GAS float* xsrc, const GAS float* csrc, GAS float* xdst, GAS float* cdst, bool xs16, bool xd16) {
;     ...
;         if (has_pre) {
;             float ss = 0.f;
; #pragma unroll
;             for (int j = 0; j < 4; ++j) ss += (v[j][0] * v[j][0] + v[j][1] * v[j][1]) + (v[j][2] * v[j][2] + v[j][3] * v[j][3]);
;             const float r = rsqrtf(wave_sum(ss) * (1.0f / 1024.0f) + EPS);
; #pragma unroll
;             for (int j = 0; j < 4; ++j) { const f32x4 h = ((v[j] * r) * gpr[j]) * (1.0f + sc[j]) + sh[j];
;                 u32x2 w; w.x = pk2(h[0], h[1]); w.y = pk2(h[2], h[3]); *(GAS u32x2*)(H + (size_t)row * 1024 + 256 * j + 4 * lane) = w; }
;         }
.LBB0_2209:
	v_pk_mul_f32 v[54:55], v[132:133], v[132:133]
	v_pk_mul_f32 v[56:57], v[130:131], v[130:131]
	v_pk_mul_f32 v[50:51], v[136:137], v[136:137]
	v_pk_mul_f32 v[52:53], v[134:135], v[134:135]
	v_pk_mov_b32 v[58:59], v[56:57], v[54:55] op_sel:[1,0]
	v_mov_b32_e32 v57, v55
	v_pk_add_f32 v[54:55], v[58:59], v[56:57]
	v_pk_mov_b32 v[56:57], v[52:53], v[50:51] op_sel:[1,0]
	v_mov_b32_e32 v53, v51
	v_pk_add_f32 v[50:51], v[56:57], v[52:53]
	v_pk_add_f32 v[54:55], v[54:55], v[54:55] op_sel_hi:[0,1]
	v_pk_add_f32 v[50:51], v[50:51], v[50:51] op_sel_hi:[0,1]
	v_mul_f32_e32 v50, v138, v138
	v_pk_fma_f32 v[52:53], v[138:139], v[138:139], v[50:51] op_sel_hi:[1,1,0]
	v_mul_f32_e32 v50, v140, v140
	v_pk_fma_f32 v[56:57], v[140:141], v[140:141], v[50:51] op_sel_hi:[1,1,0]
	v_mul_f32_e32 v52, v142, v142
	v_mul_f32_e32 v56, v143, v143
	v_mul_f32_e32 v54, v144, v144
	v_mul_f32_e32 v50, v145, v145
	v_pk_add_f32 v[52:53], v[52:53], v[56:57]
	v_pk_add_f32 v[50:51], v[54:55], v[50:51]
	s_waitcnt vmcnt(10)
	v_pk_add_f32 v[54:55], v[70:71], 1.0 op_sel_hi:[1,0]
	v_pk_add_f32 v[50:51], v[52:53], v[50:51]
	v_pk_add_f32 v[52:53], v[72:73], 1.0 op_sel_hi:[1,0]
	v_add_f32_e32 v50, v50, v51
	s_nop 1
	v_add_f32_dpp v50, v50, v50 quad_perm:[1,0,3,2] row_mask:0xf bank_mask:0xf
	s_nop 1
	v_add_f32_dpp v50, v50, v50 quad_perm:[2,3,0,1] row_mask:0xf bank_mask:0xf
	s_nop 1
	v_add_f32_dpp v50, v50, v50 row_half_mirror row_mask:0xf bank_mask:0xf
	s_nop 1
	v_add_f32_dpp v50, v50, v50 row_mirror row_mask:0xf bank_mask:0xf
	s_nop 1
	v_add_f32_dpp v50, v50, v50 row_bcast:15 row_mask:0xa bank_mask:0xf
	s_nop 1
	v_add_f32_dpp v50, v50, v50 row_bcast:31 row_mask:0xc bank_mask:0xf
	s_nop 0
	v_readlane_b32 s64, v50, 63
	s_nop 1
	v_mov_b32_e32 v50, s64
	s_waitcnt lgkmcnt(0)
	s_add_i32 s16, s16, 8
	s_cmp_lt_i32 s16, s17
	v_fmamk_f32 v50, v50, 0x3a800000, v197
	v_mul_f32_e32 v51, 0x4b800000, v50
	v_cmp_gt_f32_e32 vcc, s22, v50
	s_nop 1
	v_cndmask_b32_e32 v50, v50, v51, vcc
	v_rsq_f32_e32 v56, v50
	v_lshl_add_u64 v[50:51], v[162:163], 0, s[8:9]
	v_mul_f32_e32 v57, 0x45800000, v56
	v_cndmask_b32_e32 v56, v56, v57, vcc
	v_pk_mul_f32 v[58:59], v[132:133], v[56:57] op_sel_hi:[1,0]
	v_pk_mul_f32 v[60:61], v[130:131], v[56:57] op_sel_hi:[1,0]
	v_pk_mul_f32 v[58:59], v[12:13], v[58:59]
	v_pk_mul_f32 v[60:61], v[10:11], v[60:61]
	s_waitcnt vmcnt(9)
	v_pk_fma_f32 v[52:53], v[52:53], v[58:59], v[76:77]
	v_pk_fma_f32 v[54:55], v[54:55], v[60:61], v[74:75]
	v_pk_mul_f32 v[62:63], v[136:137], v[56:57] op_sel_hi:[1,0]
	v_pk_mul_f32 v[64:65], v[134:135], v[56:57] op_sel_hi:[1,0]
	v_cvt_pk_bf16_f32 v54, v54, v55
	v_cvt_pk_bf16_f32 v55, v52, v53
	v_pk_mul_f32 v[64:65], v[14:15], v[64:65]
	global_store_dwordx2 v[50:51], v[54:55], off
	v_pk_mul_f32 v[52:53], v[16:17], v[62:63]
	s_waitcnt vmcnt(6)
	v_pk_add_f32 v[54:55], v[80:81], 1.0 op_sel_hi:[1,0]
	v_pk_add_f32 v[58:59], v[78:79], 1.0 op_sel_hi:[1,0]
	v_pk_fma_f32 v[52:53], v[54:55], v[52:53], v[84:85]
	v_pk_fma_f32 v[54:55], v[58:59], v[64:65], v[82:83]
	s_waitcnt vmcnt(4)
	v_pk_add_f32 v[58:59], v[88:89], 1.0 op_sel_hi:[1,0]
	v_cvt_pk_bf16_f32 v54, v54, v55
	v_cvt_pk_bf16_f32 v55, v52, v53
	global_store_dwordx2 v[50:51], v[54:55], off offset:512
	v_pk_mul_f32 v[52:53], v[140:141], v[56:57] op_sel_hi:[1,0]
	v_pk_mul_f32 v[54:55], v[138:139], v[56:57] op_sel_hi:[1,0]
	v_pk_mul_f32 v[52:53], v[28:29], v[52:53]
	v_pk_mul_f32 v[54:55], v[26:27], v[54:55]
	v_pk_add_f32 v[60:61], v[86:87], 1.0 op_sel_hi:[1,0]
	s_waitcnt vmcnt(3)
	v_pk_fma_f32 v[52:53], v[58:59], v[52:53], v[96:97]
	v_pk_fma_f32 v[54:55], v[60:61], v[54:55], v[94:95]
	v_pk_add_f32 v[58:59], v[66:67], 1.0 op_sel_hi:[1,0]
	v_cvt_pk_bf16_f32 v54, v54, v55
	v_cvt_pk_bf16_f32 v55, v52, v53
	global_store_dwordx2 v[50:51], v[54:55], off offset:1024
	v_pk_mul_f32 v[52:53], v[144:145], v[56:57] op_sel_hi:[1,0]
	v_pk_mul_f32 v[54:55], v[142:143], v[56:57] op_sel_hi:[1,0]
	v_pk_mul_f32 v[52:53], v[32:33], v[52:53]
	v_pk_mul_f32 v[54:55], v[30:31], v[54:55]
	v_pk_add_f32 v[56:57], v[68:69], 1.0 op_sel_hi:[1,0]
	s_waitcnt vmcnt(3)
	v_pk_fma_f32 v[54:55], v[58:59], v[54:55], v[90:91]
	v_pk_fma_f32 v[52:53], v[56:57], v[52:53], v[92:93]
	v_cvt_pk_bf16_f32 v54, v54, v55
	v_cvt_pk_bf16_f32 v55, v52, v53
	global_store_dwordx2 v[50:51], v[54:55], off offset:1536
	s_mov_b64 vcc, s[98:99]
	s_cbranch_vccz .Leload_skip_3
	s_waitcnt vmcnt(8)
	v_lshlrev_b32_e32 v114, 16, v116
	v_and_b32_e32 v115, 0xffff0000, v116
	v_lshlrev_b32_e32 v116, 16, v117
	v_and_b32_e32 v117, 0xffff0000, v117
	v_lshlrev_b32_e32 v118, 16, v120
	v_and_b32_e32 v119, 0xffff0000, v120
	v_lshlrev_b32_e32 v120, 16, v121
	v_and_b32_e32 v121, 0xffff0000, v121
	v_lshlrev_b32_e32 v122, 16, v124
	v_and_b32_e32 v123, 0xffff0000, v124
	v_lshlrev_b32_e32 v124, 16, v125
	v_and_b32_e32 v125, 0xffff0000, v125
	v_lshlrev_b32_e32 v126, 16, v128
	v_and_b32_e32 v127, 0xffff0000, v128
	v_lshlrev_b32_e32 v128, 16, v129
	v_and_b32_e32 v129, 0xffff0000, v129

; #define GAS __attribute__((address_space(1)))
; DI unsigned pk2(float lo, float hi) { f32x2_t v = {lo, hi}; bf16x2_t b = __builtin_convertvector(v, bf16x2_t); return __builtin_bit_cast(unsigned, b); }
; DI float bflo(unsigned w) { return __uint_as_float(w << 16); }
; DI float bfhi(unsigned w) { return __uint_as_float(w & 0xffff0000u); }
; DI void phase_e(const Ctx& C, int nslab, int has_post, int pl, int ps, float pw, int has_pre, int ql, int qs, int nrows,
;                 const GAS float* xsrc, const GAS float* csrc, GAS float* xdst, GAS float* cdst, bool xs16, bool xd16) {
;     ...
;         if (has_post) {
;             f32x4 y[4]; float ss = 0.f;
; #pragma unroll
;             for (int j = 0; j < 4; ++j) {
;                 if (isx || nslab == 0) { y[j] = (f32x4){bflo(yw[j].x), bfhi(yw[j].x), bflo(yw[j].y), bfhi(yw[j].y)}; }
;                 else { y[j] = (f32x4){0.f, 0.f, 0.f, 0.f};
;                     for (int s = 0; s < nslab; ++s) { const u32x2 w = *(const GAS u32x2*)(YS + ((size_t)s * MC + (row - MX)) * 1024 + 256 * j + 4 * lane); y[j] += (f32x4){bflo(w.x), bfhi(w.x), bflo(w.y), bfhi(w.y)}; } }
;                 ss += (y[j][0] * y[j][0] + y[j][1] * y[j][1]) + (y[j][2] * y[j][2] + y[j][3] * y[j][3]); }
;             const float r = rsqrtf(wave_sum(ss) * (1.0f / 1024.0f) + EPS);
;             if (isx && xd16) { GAS bf16* d16 = (GAS bf16*)xdst + (size_t)row * 1024;
; #pragma unroll
;                 for (int j = 0; j < 4; ++j) { v[j] += pw * gt[j] * ((y[j] * r) * gpo[j]); u32x2 w; w.x = pk2(v[j][0], v[j][1]); w.y = pk2(v[j][2], v[j][3]); __builtin_nontemporal_store(w, (GAS u32x2*)(d16 + 256 * j + 4 * lane));
;                     v[j] = (f32x4){bflo(w.x), bfhi(w.x), bflo(w.y), bfhi(w.y)}; }
;             } else { GAS float* dst = isx ? xdst + (size_t)row * 1024 : cdst + (size_t)(row - MX) * 1024;
; #pragma unroll
;                 for (int j = 0; j < 4; ++j) { v[j] += pw * gt[j] * ((y[j] * r) * gpo[j]); __builtin_nontemporal_store(v[j], (GAS f32x4*)(dst + 256 * j + 4 * lane)); } }
.LBB0_2218:
	v_and_b32_e32 v189, 0xffff0000, v137
	v_and_b32_e32 v188, 0xffff0000, v136
	v_and_b32_e32 v185, 0xffff0000, v135
	v_and_b32_e32 v184, 0xffff0000, v134
	v_lshlrev_b32_e32 v187, 16, v137
	v_lshlrev_b32_e32 v186, 16, v136
	v_pk_mul_f32 v[136:137], v[188:189], v[188:189]
	v_lshlrev_b32_e32 v183, 16, v135
	v_lshlrev_b32_e32 v182, 16, v134
	v_pk_mul_f32 v[134:135], v[184:185], v[184:185]
	v_lshlrev_b32_e32 v178, 16, v132
	v_and_b32_e32 v179, 0xffff0000, v132
	v_lshlrev_b32_e32 v180, 16, v133
	v_lshlrev_b32_e32 v174, 16, v130
	v_pk_fma_f32 v[136:137], v[186:187], v[186:187], v[136:137]
	v_pk_fma_f32 v[134:135], v[182:183], v[182:183], v[134:135]
	v_mul_f32_e32 v139, v178, v178
	v_mul_f32_e32 v141, v179, v179
	v_and_b32_e32 v181, 0xffff0000, v133
	v_mul_f32_e32 v132, v180, v180
	v_mov_b32_e32 v138, v174
	v_mov_b32_e32 v140, v174
	v_pk_add_f32 v[136:137], v[136:137], v[136:137] op_sel_hi:[0,1]
	v_pk_add_f32 v[134:135], v[134:135], v[134:135] op_sel_hi:[0,1]
	v_pk_fma_f32 v[132:133], v[180:181], v[180:181], v[132:133] op_sel_hi:[1,1,0]
	v_and_b32_e32 v175, 0xffff0000, v130
	v_lshlrev_b32_e32 v176, 16, v131
	v_and_b32_e32 v177, 0xffff0000, v131
	v_pk_add_f32 v[138:139], v[138:139], v[140:141]
	v_mul_f32_e32 v132, v175, v175
	v_mul_f32_e32 v134, v176, v176
	v_mul_f32_e32 v136, v177, v177
	v_mul_f32_e32 v130, v174, v174
	v_mov_b32_e32 v131, v139
	v_pk_add_f32 v[130:131], v[130:131], v[132:133]
	v_pk_add_f32 v[132:133], v[134:135], v[136:137]
	s_ashr_i32 s7, s6, 31
	v_pk_add_f32 v[130:131], v[130:131], v[132:133]
	s_cmpk_gt_i32 s6, 0x7fff
	v_add_f32_e32 v130, v130, v131
	s_nop 1
	v_add_f32_dpp v130, v130, v130 quad_perm:[1,0,3,2] row_mask:0xf bank_mask:0xf
	s_nop 1
	v_add_f32_dpp v130, v130, v130 quad_perm:[2,3,0,1] row_mask:0xf bank_mask:0xf
	s_nop 1
	v_add_f32_dpp v130, v130, v130 row_half_mirror row_mask:0xf bank_mask:0xf
	s_nop 1
	v_add_f32_dpp v130, v130, v130 row_mirror row_mask:0xf bank_mask:0xf
	s_nop 1
	v_add_f32_dpp v130, v130, v130 row_bcast:15 row_mask:0xa bank_mask:0xf
	s_nop 1
	v_add_f32_dpp v130, v130, v130 row_bcast:31 row_mask:0xc bank_mask:0xf
	s_nop 0
	v_readlane_b32 s64, v130, 63
	s_nop 1
	v_mov_b32_e32 v130, s64
	s_waitcnt lgkmcnt(0)
	s_mov_b64 s[10:11], -1
	v_fmamk_f32 v130, v130, 0x3a800000, v197
	v_mul_f32_e32 v131, 0x4b800000, v130
	v_cmp_gt_f32_e32 vcc, s22, v130
	s_nop 1
	v_cndmask_b32_e32 v130, v130, v131, vcc
	v_rsq_f32_e32 v130, v130
	s_nop 0
	v_mul_f32_e32 v131, 0x45800000, v130
	v_cndmask_b32_e32 v190, v130, v131, vcc
	s_cbranch_scc0 .LBB0_2220
	v_mov_b32_e32 v130, v187
	v_mov_b32_e32 v131, v189
	v_mov_b32_e32 v132, v186
	v_mov_b32_e32 v133, v188
	v_pk_mul_f32 v[130:131], v[130:131], v[190:191] op_sel_hi:[1,0]
	v_pk_mul_f32 v[132:133], v[132:133], v[190:191] op_sel_hi:[1,0]
	v_pk_mul_f32 v[130:131], v[4:5], v[130:131]
	v_pk_mul_f32 v[134:135], v[2:3], v[132:133]
	s_waitcnt vmcnt(11)
	v_pk_fma_f32 v[132:133], v[100:101], v[130:131], v[64:65]
	v_pk_fma_f32 v[130:131], v[98:99], v[134:135], v[62:63]
	v_mov_b32_e32 v134, v183
	v_mov_b32_e32 v135, v185
	v_mov_b32_e32 v136, v182
	v_mov_b32_e32 v137, v184
	v_pk_mul_f32 v[134:135], v[134:135], v[190:191] op_sel_hi:[1,0]
	v_pk_mul_f32 v[136:137], v[136:137], v[190:191] op_sel_hi:[1,0]
	v_pk_mul_f32 v[134:135], v[8:9], v[134:135]
	v_pk_mul_f32 v[138:139], v[6:7], v[136:137]
	s_add_i32 s0, s6, 0xffff8000
	s_waitcnt vmcnt(7)
	v_pk_fma_f32 v[136:137], v[104:105], v[134:135], v[60:61]
	v_pk_fma_f32 v[134:135], v[102:103], v[138:139], v[58:59]
	v_pk_mul_f32 v[138:139], v[178:179], v[190:191] op_sel_hi:[1,0]
	v_pk_mul_f32 v[140:141], v[180:181], v[190:191] op_sel_hi:[1,0]
	v_pk_mul_f32 v[142:143], v[176:177], v[190:191] op_sel_hi:[1,0]
	v_pk_mul_f32 v[144:145], v[174:175], v[190:191] op_sel_hi:[1,0]
	s_lshl_b64 s[8:9], s[0:1], 12
	v_pk_mul_f32 v[138:139], v[18:19], v[138:139]
	v_pk_mul_f32 v[140:141], v[20:21], v[140:141]
	v_pk_mul_f32 v[200:201], v[22:23], v[144:145]
	v_pk_mul_f32 v[142:143], v[24:25], v[142:143]
	v_lshl_add_u64 v[198:199], v[164:165], 0, s[8:9]
	s_waitcnt vmcnt(6)
	v_pk_fma_f32 v[140:141], v[108:109], v[140:141], v[56:57]
	v_pk_fma_f32 v[138:139], v[106:107], v[138:139], v[54:55]
	s_waitcnt vmcnt(4)
	v_pk_fma_f32 v[144:145], v[112:113], v[142:143], v[52:53]
	v_pk_fma_f32 v[142:143], v[110:111], v[200:201], v[50:51]
	global_store_dwordx4 v[198:199], v[130:133], off nt
	global_store_dwordx4 v[198:199], v[134:137], off offset:1024 nt
	global_store_dwordx4 v[198:199], v[138:141], off offset:2048 nt
	global_store_dwordx4 v[198:199], v[142:145], off offset:3072 nt
	s_lshl_b64 s[8:9], s[6:7], 11
	s_mov_b64 s[10:11], 0

; #define GAS __attribute__((address_space(1)))
; DI unsigned pk2(float lo, float hi) { f32x2_t v = {lo, hi}; bf16x2_t b = __builtin_convertvector(v, bf16x2_t); return __builtin_bit_cast(unsigned, b); }
; DI float bflo(unsigned w) { return __uint_as_float(w << 16); }
; DI float bfhi(unsigned w) { return __uint_as_float(w & 0xffff0000u); }
; DI void phase_e(const Ctx& C, int nslab, int has_post, int pl, int ps, float pw, int has_pre, int ql, int qs, int nrows,
;                 const GAS float* xsrc, const GAS float* csrc, GAS float* xdst, GAS float* cdst, bool xs16, bool xd16) {
;     ...
;         if (has_post) {
;             f32x4 y[4]; float ss = 0.f;
; #pragma unroll
;             for (int j = 0; j < 4; ++j) {
;                 if (isx || nslab == 0) { y[j] = (f32x4){bflo(yw[j].x), bfhi(yw[j].x), bflo(yw[j].y), bfhi(yw[j].y)}; }
;                 else { y[j] = (f32x4){0.f, 0.f, 0.f, 0.f};
;                     for (int s = 0; s < nslab; ++s) { const u32x2 w = *(const GAS u32x2*)(YS + ((size_t)s * MC + (row - MX)) * 1024 + 256 * j + 4 * lane); y[j] += (f32x4){bflo(w.x), bfhi(w.x), bflo(w.y), bfhi(w.y)}; } }
;                 ss += (y[j][0] * y[j][0] + y[j][1] * y[j][1]) + (y[j][2] * y[j][2] + y[j][3] * y[j][3]); }
;             const float r = rsqrtf(wave_sum(ss) * (1.0f / 1024.0f) + EPS);
;             if (isx && xd16) { GAS bf16* d16 = (GAS bf16*)xdst + (size_t)row * 1024;
; #pragma unroll
;                 for (int j = 0; j < 4; ++j) { v[j] += pw * gt[j] * ((y[j] * r) * gpo[j]); u32x2 w; w.x = pk2(v[j][0], v[j][1]); w.y = pk2(v[j][2], v[j][3]); __builtin_nontemporal_store(w, (GAS u32x2*)(d16 + 256 * j + 4 * lane));
;                     v[j] = (f32x4){bflo(w.x), bfhi(w.x), bflo(w.y), bfhi(w.y)}; }
;             } else { GAS float* dst = isx ? xdst + (size_t)row * 1024 : cdst + (size_t)(row - MX) * 1024;
; #pragma unroll
;                 for (int j = 0; j < 4; ++j) { v[j] += pw * gt[j] * ((y[j] * r) * gpo[j]); __builtin_nontemporal_store(v[j], (GAS f32x4*)(dst + 256 * j + 4 * lane)); } }
.LBB0_2444:
	v_lshlrev_b32_e32 v123, 16, v99
	v_lshlrev_b32_e32 v122, 16, v98
	v_and_b32_e32 v99, 0xffff0000, v99
	v_and_b32_e32 v98, 0xffff0000, v98
	v_pk_mul_f32 v[124:125], v[98:99], v[98:99]
	v_lshlrev_b32_e32 v127, 16, v91
	v_pk_fma_f32 v[124:125], v[122:123], v[122:123], v[124:125]
	v_lshlrev_b32_e32 v126, 16, v90
	v_and_b32_e32 v91, 0xffff0000, v91
	v_and_b32_e32 v90, 0xffff0000, v90
	v_pk_add_f32 v[124:125], v[124:125], v[124:125] op_sel_hi:[0,1]
	v_pk_mul_f32 v[128:129], v[90:91], v[90:91]
	v_lshlrev_b32_e32 v130, 16, v86
	v_and_b32_e32 v131, 0xffff0000, v86
	v_lshlrev_b32_e32 v86, 16, v87
	v_lshlrev_b32_e32 v132, 16, v84
	v_pk_fma_f32 v[128:129], v[126:127], v[126:127], v[128:129]
	v_mul_f32_e32 v133, v130, v130
	v_mul_f32_e32 v135, v131, v131
	v_and_b32_e32 v87, 0xffff0000, v87
	v_mul_f32_e32 v124, v86, v86
	v_mov_b32_e32 v134, v132
	v_pk_add_f32 v[128:129], v[128:129], v[128:129] op_sel_hi:[0,1]
	v_pk_fma_f32 v[136:137], v[86:87], v[86:87], v[124:125] op_sel_hi:[1,1,0]
	v_and_b32_e32 v121, 0xffff0000, v84
	v_lshlrev_b32_e32 v84, 16, v85
	v_and_b32_e32 v85, 0xffff0000, v85
	v_pk_add_f32 v[134:135], v[132:133], v[134:135]
	v_mul_f32_e32 v136, v121, v121
	v_mul_f32_e32 v128, v84, v84
	v_mul_f32_e32 v124, v85, v85
	v_mul_f32_e32 v138, v132, v132
	v_mov_b32_e32 v139, v135
	v_pk_add_f32 v[134:135], v[138:139], v[136:137]
	v_pk_add_f32 v[124:125], v[128:129], v[124:125]
	s_add_i32 s2, s19, 0xffff8000
	v_pk_add_f32 v[124:125], v[134:135], v[124:125]
	s_ashr_i32 s6, s19, 31
	v_add_f32_e32 v124, v124, v125
	s_nop 1
	v_add_f32_dpp v124, v124, v124 quad_perm:[1,0,3,2] row_mask:0xf bank_mask:0xf
	s_nop 1
	v_add_f32_dpp v124, v124, v124 quad_perm:[2,3,0,1] row_mask:0xf bank_mask:0xf
	s_nop 1
	v_add_f32_dpp v124, v124, v124 row_half_mirror row_mask:0xf bank_mask:0xf
	s_nop 1
	v_add_f32_dpp v124, v124, v124 row_mirror row_mask:0xf bank_mask:0xf
	s_nop 1
	v_add_f32_dpp v124, v124, v124 row_bcast:15 row_mask:0xa bank_mask:0xf
	s_nop 1
	v_add_f32_dpp v124, v124, v124 row_bcast:31 row_mask:0xc bank_mask:0xf
	s_nop 0
	v_readlane_b32 s64, v124, 63
	s_nop 1
	v_mov_b32_e32 v124, s64
	s_waitcnt lgkmcnt(0)
	s_cmp_lt_i32 s19, 0x8000
	v_mov_b32_e32 v136, v123
	v_mov_b32_e32 v123, v98
	s_cselect_b32 s7, s6, 0
	s_cselect_b32 s6, s19, s2
	v_mov_b32_e32 v137, v99
	s_cselect_b32 s2, s75, s1
	s_cselect_b32 s8, s74, s0
	s_lshl_b64 s[6:7], s[6:7], 12
	s_waitcnt vmcnt(1)
	v_pk_mul_f32 v[134:135], v[50:51], 0.5 op_sel_hi:[1,0]
	s_add_u32 s6, s8, s6
	v_pk_mul_f32 v[128:129], v[52:53], 0.5 op_sel_hi:[1,0]
	s_addc_u32 s7, s2, s7
	v_mov_b32_e32 v133, v121
	s_add_i32 s14, s14, 8
	s_cmp_lt_i32 s14, s15
	v_fmamk_f32 v124, v124, 0x3a800000, v120
	v_mul_f32_e32 v125, 0x4b800000, v124
	v_cmp_gt_f32_e32 vcc, s18, v124
	s_nop 1
	v_cndmask_b32_e32 v124, v124, v125, vcc
	v_rsq_f32_e32 v124, v124
	s_nop 0
	v_mul_f32_e32 v125, 0x45800000, v124
	v_cndmask_b32_e32 v124, v124, v125, vcc
	v_pk_mul_f32 v[98:99], v[122:123], v[124:125] op_sel_hi:[1,0]
	v_pk_mul_f32 v[136:137], v[136:137], v[124:125] op_sel_hi:[1,0]
	v_pk_mul_f32 v[98:99], v[2:3], v[98:99]
	v_pk_mul_f32 v[122:123], v[4:5], v[136:137]
	v_pk_fma_f32 v[30:31], v[134:135], v[98:99], v[30:31]
	v_mov_b32_e32 v98, v127
	v_mov_b32_e32 v99, v91
	v_mov_b32_e32 v127, v90
	v_pk_fma_f32 v[32:33], v[128:129], v[122:123], v[32:33]
	v_pk_mul_f32 v[98:99], v[98:99], v[124:125] op_sel_hi:[1,0]
	v_pk_mul_f32 v[90:91], v[126:127], v[124:125] op_sel_hi:[1,0]
	global_store_dwordx4 v82, v[30:33], s[6:7] nt
	v_pk_mul_f32 v[90:91], v[6:7], v[90:91]
	v_pk_mul_f32 v[98:99], v[8:9], v[98:99]
	v_pk_mul_f32 v[30:31], v[56:57], 0.5 op_sel_hi:[1,0]
	v_pk_mul_f32 v[32:33], v[54:55], 0.5 op_sel_hi:[1,0]
	v_pk_fma_f32 v[28:29], v[30:31], v[98:99], v[28:29]
	v_pk_fma_f32 v[26:27], v[32:33], v[90:91], v[26:27]
	v_pk_mul_f32 v[30:31], v[86:87], v[124:125] op_sel_hi:[1,0]
	v_pk_mul_f32 v[32:33], v[130:131], v[124:125] op_sel_hi:[1,0]
	global_store_dwordx4 v82, v[26:29], s[6:7] offset:1024 nt
	v_pk_mul_f32 v[32:33], v[10:11], v[32:33]
	v_pk_mul_f32 v[30:31], v[12:13], v[30:31]
	v_pk_mul_f32 v[26:27], v[60:61], 0.5 op_sel_hi:[1,0]
	v_pk_mul_f32 v[28:29], v[58:59], 0.5 op_sel_hi:[1,0]
	v_pk_fma_f32 v[24:25], v[26:27], v[30:31], v[24:25]
	v_pk_fma_f32 v[22:23], v[28:29], v[32:33], v[22:23]
	v_pk_mul_f32 v[26:27], v[84:85], v[124:125] op_sel_hi:[1,0]
	v_pk_mul_f32 v[28:29], v[132:133], v[124:125] op_sel_hi:[1,0]
	global_store_dwordx4 v82, v[22:25], s[6:7] offset:2048 nt
	v_pk_mul_f32 v[28:29], v[14:15], v[28:29]
	v_pk_mul_f32 v[26:27], v[16:17], v[26:27]
	s_waitcnt vmcnt(3)
	v_pk_mul_f32 v[22:23], v[64:65], 0.5 op_sel_hi:[1,0]
	v_pk_mul_f32 v[24:25], v[62:63], 0.5 op_sel_hi:[1,0]
	v_pk_fma_f32 v[20:21], v[22:23], v[26:27], v[20:21]
	v_pk_fma_f32 v[18:19], v[24:25], v[28:29], v[18:19]
	global_store_dwordx4 v82, v[18:21], s[6:7] offset:3072 nt
	s_mov_b64 vcc, s[98:99]
	s_cbranch_vccz .Leload_skip_4
	s_waitcnt vmcnt(4)
	v_lshlrev_b32_e32 v66, 16, v68
	v_and_b32_e32 v67, 0xffff0000, v68
	v_lshlrev_b32_e32 v68, 16, v69
	v_and_b32_e32 v69, 0xffff0000, v69
	v_lshlrev_b32_e32 v70, 16, v72
	v_and_b32_e32 v71, 0xffff0000, v72
	v_lshlrev_b32_e32 v72, 16, v73
	v_and_b32_e32 v73, 0xffff0000, v73
	v_lshlrev_b32_e32 v74, 16, v76
	v_and_b32_e32 v75, 0xffff0000, v76
	v_lshlrev_b32_e32 v76, 16, v77
	v_and_b32_e32 v77, 0xffff0000, v77
	v_lshlrev_b32_e32 v78, 16, v80
	v_and_b32_e32 v79, 0xffff0000, v80
	v_lshlrev_b32_e32 v80, 16, v81
	v_and_b32_e32 v81, 0xffff0000, v81
